# on top of best: all s_setprio flips removed from the GEMM K-loops
# speedup vs baseline: 1.0082x; 1.0003x over previous
; #define PG8_STAGE(bufoff, gbase, voff) do { _Pragma("unroll") for (int _i = 0; _i < 2; ++_i) \
;         __builtin_amdgcn_global_load_lds((const unsigned*)((const char*)(gbase) + (voff)[_i]), (PG8_LAS unsigned*)(lds + (bufoff) + ldsw + _i * 8192), 16, 0, 0); } while (0)
; #define PG8_LDA(dst, b, h) do { _Pragma("unroll") for (int m = 0; m < 4; ++m) _Pragma("unroll") for (int k = 0; k < 2; ++k) dst[m][k] = *(const PG8_LAS bf16x8*)(lds + PG8_SA(b, h) + aoff + m * 2048 + k * 1024); } while (0)
; #define PG8_LDB(dst, b, h) do { _Pragma("unroll") for (int n = 0; n < 2; ++n) _Pragma("unroll") for (int k = 0; k < 2; ++k) dst[n][k] = *(const PG8_LAS bf16x8*)(lds + PG8_SB(b, h) + boff + n * 2048 + k * 1024); } while (0)
; #define PG8_MMA(ai, bj, At, Bt) do { __builtin_amdgcn_s_setprio(1); _Pragma("unroll") for (int m = 0; m < 4; ++m) _Pragma("unroll") for (int n = 0; n < 2; ++n) _Pragma("unroll") for (int k = 0; k < 2; ++k) \
;         acc[ai][bj][m][n] = __builtin_amdgcn_mfma_f32_16x16x32_bf16(Bt[n][k], At[m][k], acc[ai][bj][m][n], 0, 0, 0); __builtin_amdgcn_s_setprio(0); } while (0)
; #define PG8_WAIT_V(n) asm volatile("s_waitcnt vmcnt(" #n ")" ::: "memory")
; #define PG8_WAIT_L(n) asm volatile("s_waitcnt lgkmcnt(" #n ")" ::: "memory")
; #define PG8_BAR __builtin_amdgcn_s_barrier()
; template <class Epi, class Sched, bool ALIGN_EPI = false, bool SP2 = false>
; __device__ __forceinline__ void gemm_phase(PG8_LAS unsigned char* lds, const Gemm g, const Sched& S, const Epi& E) {
;     ...
;             const char* a1 = cA + (size_t)(t + 1) * kstep;
;             const char* a2 = last ? nA : cA + (size_t)(t + 2) * kstep; const char* b2 = last ? nB : cB + (size_t)(t + 2) * kstep;
;             const char* a3 = a2 + kstep; const char* b3 = b2 + kstep;
;             if (last && has_next) S.a_ready(nxt);
;             if constexpr (SP2) {
;             PG8_LDB(B0, 0, 0); PG8_LDB(B1, 0, 1); PG8_SCHED; PG8_LDA(At, 0, 0); PG8_STAGE(PG8_SA(1, 1), a1 + hstep, voffA);
;             PG8_WAIT_V(8); PG8_WAIT_L(0); PG8_BAR; PG8_MMA(0, 0, At, B0); PG8_MMA(0, 1, At, B1); PG8_BAR; PG8_SCHED;
;             PG8_LDA(At, 0, 1); PG8_STAGE(PG8_SB(0, 0), b2, voffB); PG8_STAGE(PG8_SB(0, 1), b2 + hstep, voffB); PG8_STAGE(PG8_SA(0, 0), a2, voffA);
;             PG8_WAIT_V(8); PG8_WAIT_L(0); PG8_BAR; PG8_MMA(1, 0, At, B0); PG8_MMA(1, 1, At, B1); PG8_BAR; PG8_SCHED;
.LBB0_132:
	s_add_u32 s18, s46, 0xfffc0080
	s_addc_u32 s38, s47, -1
	s_add_i32 s39, 0, 0x10000
	s_cmp_eq_u32 s85, 12
	s_cselect_b32 s81, s33, s38
	s_cselect_b32 s80, s73, s18
	v_add_u32_e32 v0, s39, v176
	s_cselect_b32 s45, s75, s84
	s_cselect_b32 s44, s82, s83
	s_add_i32 s18, 0, 0x14000
	ds_read_b128 v[144:147], v0
	ds_read_b128 v[148:151], v0 offset:1024
	ds_read_b128 v[152:155], v0 offset:2048
	ds_read_b128 v[156:159], v0 offset:3072
	v_add_u32_e32 v0, s18, v176
	ds_read_b128 v[160:163], v0
	ds_read_b128 v[164:167], v0 offset:1024
	ds_read_b128 v[168:171], v0 offset:2048
	ds_read_b128 v[172:175], v0 offset:3072
	v_lshl_add_u64 v[218:219], s[46:47], 0, v[140:141]
	s_add_i32 m0, s92, 0xc000
	ds_read_b128 v[180:183], v178
	ds_read_b128 v[184:187], v178 offset:1024
	ds_read_b128 v[188:191], v178 offset:2048
	ds_read_b128 v[192:195], v178 offset:3072
	ds_read_b128 v[202:205], v178 offset:4096
	ds_read_b128 v[206:209], v178 offset:5120
	ds_read_b128 v[210:213], v178 offset:6144
	ds_read_b128 v[214:217], v178 offset:7168
	global_load_lds_dwordx4 v[218:219], off
	v_lshl_add_u64 v[218:219], s[46:47], 0, v[142:143]
	s_add_i32 m0, s92, 0xe000
	s_nop 0
	global_load_lds_dwordx4 v[218:219], off
	s_waitcnt vmcnt(8)
	s_waitcnt lgkmcnt(0)
	s_barrier
	v_mfma_f32_16x16x32_bf16 v[118:121], v[144:147], v[180:183], v[118:121]
	v_mfma_f32_16x16x32_bf16 v[118:121], v[148:151], v[184:187], v[118:121]
	v_mfma_f32_16x16x32_bf16 v[102:105], v[144:147], v[188:191], v[102:105]
	v_mfma_f32_16x16x32_bf16 v[102:105], v[148:151], v[192:195], v[102:105]
	v_mfma_f32_16x16x32_bf16 v[86:89], v[144:147], v[202:205], v[86:89]
	v_mfma_f32_16x16x32_bf16 v[86:89], v[148:151], v[206:209], v[86:89]
	v_mfma_f32_16x16x32_bf16 v[70:73], v[144:147], v[210:213], v[70:73]
	v_mfma_f32_16x16x32_bf16 v[70:73], v[148:151], v[214:217], v[70:73]
	v_mfma_f32_16x16x32_bf16 v[114:117], v[152:155], v[180:183], v[114:117]
	v_mfma_f32_16x16x32_bf16 v[114:117], v[156:159], v[184:187], v[114:117]
	v_mfma_f32_16x16x32_bf16 v[98:101], v[152:155], v[188:191], v[98:101]
	v_mfma_f32_16x16x32_bf16 v[98:101], v[156:159], v[192:195], v[98:101]
	v_mfma_f32_16x16x32_bf16 v[82:85], v[152:155], v[202:205], v[82:85]
	v_mfma_f32_16x16x32_bf16 v[82:85], v[156:159], v[206:209], v[82:85]
	v_mfma_f32_16x16x32_bf16 v[66:69], v[152:155], v[210:213], v[66:69]
	v_mfma_f32_16x16x32_bf16 v[66:69], v[156:159], v[214:217], v[66:69]
	v_mfma_f32_16x16x32_bf16 v[126:129], v[160:163], v[180:183], v[126:129]
	v_mfma_f32_16x16x32_bf16 v[126:129], v[164:167], v[184:187], v[126:129]
	v_mfma_f32_16x16x32_bf16 v[110:113], v[160:163], v[188:191], v[110:113]
	v_mfma_f32_16x16x32_bf16 v[110:113], v[164:167], v[192:195], v[110:113]
	v_mfma_f32_16x16x32_bf16 v[94:97], v[160:163], v[202:205], v[94:97]
	v_mfma_f32_16x16x32_bf16 v[94:97], v[164:167], v[206:209], v[94:97]
	v_mfma_f32_16x16x32_bf16 v[78:81], v[160:163], v[210:213], v[78:81]
	v_mfma_f32_16x16x32_bf16 v[78:81], v[164:167], v[214:217], v[78:81]
	v_mfma_f32_16x16x32_bf16 v[122:125], v[168:171], v[180:183], v[122:125]
	v_mfma_f32_16x16x32_bf16 v[122:125], v[172:175], v[184:187], v[122:125]
	v_mfma_f32_16x16x32_bf16 v[106:109], v[168:171], v[188:191], v[106:109]
	v_mfma_f32_16x16x32_bf16 v[106:109], v[172:175], v[192:195], v[106:109]
	v_mfma_f32_16x16x32_bf16 v[90:93], v[168:171], v[202:205], v[90:93]
	v_mfma_f32_16x16x32_bf16 v[90:93], v[172:175], v[206:209], v[90:93]
	v_mfma_f32_16x16x32_bf16 v[74:77], v[168:171], v[210:213], v[74:77]
	v_mfma_f32_16x16x32_bf16 v[74:77], v[172:175], v[214:217], v[74:77]
	s_barrier
	s_add_i32 s38, s39, s91
	v_lshl_add_u64 v[218:219], s[44:45], 0, v[134:135]
	s_mov_b32 m0, s38
	ds_read_b128 v[180:183], v178 offset:16384
	ds_read_b128 v[184:187], v178 offset:17408
	ds_read_b128 v[188:191], v178 offset:18432
	ds_read_b128 v[192:195], v178 offset:19456
	ds_read_b128 v[202:205], v178 offset:20480
	ds_read_b128 v[206:209], v178 offset:21504
	ds_read_b128 v[210:213], v178 offset:22528
	ds_read_b128 v[214:217], v178 offset:23552
	global_load_lds_dwordx4 v[218:219], off
	s_add_i32 m0, s38, 0x2000
	s_add_u32 s38, s44, 0x40000
	v_lshl_add_u64 v[220:221], s[44:45], 0, v[130:131]
	s_addc_u32 s39, s45, 0
	s_add_i32 s18, s18, s91
	global_load_lds_dwordx4 v[220:221], off
	v_lshl_add_u64 v[222:223], s[38:39], 0, v[134:135]
	s_mov_b32 m0, s18
	v_lshl_add_u64 v[224:225], s[80:81], 0, v[132:133]
	global_load_lds_dwordx4 v[222:223], off
	v_lshl_add_u64 v[222:223], s[38:39], 0, v[130:131]
	s_add_i32 m0, s18, 0x2000
	s_nop 0
	global_load_lds_dwordx4 v[222:223], off
	v_lshl_add_u64 v[222:223], s[80:81], 0, v[136:137]
	s_mov_b32 m0, s92
	s_nop 0
	global_load_lds_dwordx4 v[222:223], off
	s_mov_b32 m0, s93
	s_nop 0
	global_load_lds_dwordx4 v[224:225], off
	s_waitcnt vmcnt(8)
	s_waitcnt lgkmcnt(0)
	s_barrier
; #define PG8_STAGE(bufoff, gbase, voff) do { _Pragma("unroll") for (int _i = 0; _i < 2; ++_i) \
;         __builtin_amdgcn_global_load_lds((const unsigned*)((const char*)(gbase) + (voff)[_i]), (PG8_LAS unsigned*)(lds + (bufoff) + ldsw + _i * 8192), 16, 0, 0); } while (0)
; #define PG8_LDA(dst, b, h) do { _Pragma("unroll") for (int m = 0; m < 4; ++m) _Pragma("unroll") for (int k = 0; k < 2; ++k) dst[m][k] = *(const PG8_LAS bf16x8*)(lds + PG8_SA(b, h) + aoff + m * 2048 + k * 1024); } while (0)
; #define PG8_LDB(dst, b, h) do { _Pragma("unroll") for (int n = 0; n < 2; ++n) _Pragma("unroll") for (int k = 0; k < 2; ++k) dst[n][k] = *(const PG8_LAS bf16x8*)(lds + PG8_SB(b, h) + boff + n * 2048 + k * 1024); } while (0)
; #define PG8_MMA(ai, bj, At, Bt) do { __builtin_amdgcn_s_setprio(1); _Pragma("unroll") for (int m = 0; m < 4; ++m) _Pragma("unroll") for (int n = 0; n < 2; ++n) _Pragma("unroll") for (int k = 0; k < 2; ++k) \
;         acc[ai][bj][m][n] = __builtin_amdgcn_mfma_f32_16x16x32_bf16(Bt[n][k], At[m][k], acc[ai][bj][m][n], 0, 0, 0); __builtin_amdgcn_s_setprio(0); } while (0)
; #define PG8_WAIT_V(n) asm volatile("s_waitcnt vmcnt(" #n ")" ::: "memory")
; #define PG8_WAIT_L(n) asm volatile("s_waitcnt lgkmcnt(" #n ")" ::: "memory")
; #define PG8_BAR __builtin_amdgcn_s_barrier()
; #define PG8_SCHED __builtin_amdgcn_sched_barrier(0)
; template <class Epi, class Sched, bool ALIGN_EPI = false, bool SP2 = false>
; __device__ __forceinline__ void gemm_phase(PG8_LAS unsigned char* lds, const Gemm g, const Sched& S, const Epi& E) {
;     ...
;             PG8_WAIT_V(8); PG8_WAIT_L(0); PG8_BAR; PG8_MMA(1, 0, At, B0); PG8_MMA(1, 1, At, B1); PG8_BAR; PG8_SCHED;
;             PG8_LDB(B0, 1, 0); PG8_LDB(B1, 1, 1); PG8_SCHED; PG8_LDA(At, 1, 0); PG8_STAGE(PG8_SA(0, 1), a2 + hstep, voffA);
;             PG8_WAIT_V(8); PG8_WAIT_L(0); PG8_BAR; PG8_MMA(0, 0, At, B0); PG8_MMA(0, 1, At, B1); PG8_BAR; PG8_SCHED;
	v_mfma_f32_16x16x32_bf16 v[54:57], v[144:147], v[180:183], v[54:57]
	v_mfma_f32_16x16x32_bf16 v[54:57], v[148:151], v[184:187], v[54:57]
	v_mfma_f32_16x16x32_bf16 v[38:41], v[144:147], v[188:191], v[38:41]
	v_mfma_f32_16x16x32_bf16 v[38:41], v[148:151], v[192:195], v[38:41]
	v_mfma_f32_16x16x32_bf16 v[22:25], v[144:147], v[202:205], v[22:25]
	v_mfma_f32_16x16x32_bf16 v[22:25], v[148:151], v[206:209], v[22:25]
	v_mfma_f32_16x16x32_bf16 v[6:9], v[144:147], v[210:213], v[6:9]
	v_mfma_f32_16x16x32_bf16 v[6:9], v[148:151], v[214:217], v[6:9]
	v_mfma_f32_16x16x32_bf16 v[50:53], v[152:155], v[180:183], v[50:53]
	v_mfma_f32_16x16x32_bf16 v[50:53], v[156:159], v[184:187], v[50:53]
	v_mfma_f32_16x16x32_bf16 v[34:37], v[152:155], v[188:191], v[34:37]
	v_mfma_f32_16x16x32_bf16 v[34:37], v[156:159], v[192:195], v[34:37]
	v_mfma_f32_16x16x32_bf16 v[18:21], v[152:155], v[202:205], v[18:21]
	v_mfma_f32_16x16x32_bf16 v[18:21], v[156:159], v[206:209], v[18:21]
	v_mfma_f32_16x16x32_bf16 v[2:5], v[152:155], v[210:213], v[2:5]
	v_mfma_f32_16x16x32_bf16 v[2:5], v[156:159], v[214:217], v[2:5]
	v_mfma_f32_16x16x32_bf16 v[62:65], v[160:163], v[180:183], v[62:65]
	v_mfma_f32_16x16x32_bf16 v[62:65], v[164:167], v[184:187], v[62:65]
	v_mfma_f32_16x16x32_bf16 v[46:49], v[160:163], v[188:191], v[46:49]
	v_mfma_f32_16x16x32_bf16 v[46:49], v[164:167], v[192:195], v[46:49]
	v_mfma_f32_16x16x32_bf16 v[30:33], v[160:163], v[202:205], v[30:33]
	v_mfma_f32_16x16x32_bf16 v[30:33], v[164:167], v[206:209], v[30:33]
	v_mfma_f32_16x16x32_bf16 v[10:13], v[160:163], v[210:213], v[10:13]
	v_mfma_f32_16x16x32_bf16 v[10:13], v[164:167], v[214:217], v[10:13]
	v_mfma_f32_16x16x32_bf16 v[58:61], v[168:171], v[180:183], v[58:61]
	v_mfma_f32_16x16x32_bf16 v[58:61], v[172:175], v[184:187], v[58:61]
	v_mfma_f32_16x16x32_bf16 v[42:45], v[168:171], v[188:191], v[42:45]
	v_mfma_f32_16x16x32_bf16 v[42:45], v[172:175], v[192:195], v[42:45]
	v_mfma_f32_16x16x32_bf16 v[26:29], v[168:171], v[202:205], v[26:29]
	v_mfma_f32_16x16x32_bf16 v[26:29], v[172:175], v[206:209], v[26:29]
	v_mfma_f32_16x16x32_bf16 v[14:17], v[168:171], v[210:213], v[14:17]
	v_mfma_f32_16x16x32_bf16 v[14:17], v[172:175], v[214:217], v[14:17]
	s_barrier
	s_add_i32 s18, 0, 0x18000
	v_add_u32_e32 v0, s18, v176
	s_add_i32 vcc_lo, 0, 0x1c000
	ds_read_b128 v[144:147], v0
	ds_read_b128 v[148:151], v0 offset:1024
	ds_read_b128 v[152:155], v0 offset:2048
	ds_read_b128 v[156:159], v0 offset:3072
	v_add_u32_e32 v0, vcc_lo, v176
	ds_read_b128 v[160:163], v0
	ds_read_b128 v[164:167], v0 offset:1024
	ds_read_b128 v[168:171], v0 offset:2048
	ds_read_b128 v[172:175], v0 offset:3072
	s_add_u32 s38, s80, 0x40000
	s_addc_u32 s39, s81, 0
	s_mov_b32 m0, s94
	v_lshl_add_u64 v[226:227], s[38:39], 0, v[136:137]
	ds_read_b128 v[180:183], v178 offset:32768
	ds_read_b128 v[184:187], v178 offset:33792
	ds_read_b128 v[188:191], v178 offset:34816
	ds_read_b128 v[192:195], v178 offset:35840
	ds_read_b128 v[202:205], v178 offset:36864
	ds_read_b128 v[206:209], v178 offset:37888
	ds_read_b128 v[210:213], v178 offset:38912
	ds_read_b128 v[214:217], v178 offset:39936
	global_load_lds_dwordx4 v[226:227], off
	v_lshl_add_u64 v[226:227], s[38:39], 0, v[132:133]
	s_mov_b32 m0, s95
	s_nop 0
	global_load_lds_dwordx4 v[226:227], off
	s_waitcnt vmcnt(8)
	s_waitcnt lgkmcnt(0)
	s_barrier
	v_mfma_f32_16x16x32_bf16 v[118:121], v[144:147], v[180:183], v[118:121]
	v_mfma_f32_16x16x32_bf16 v[118:121], v[148:151], v[184:187], v[118:121]
	v_mfma_f32_16x16x32_bf16 v[102:105], v[144:147], v[188:191], v[102:105]
	v_mfma_f32_16x16x32_bf16 v[102:105], v[148:151], v[192:195], v[102:105]
	v_mfma_f32_16x16x32_bf16 v[86:89], v[144:147], v[202:205], v[86:89]
	v_mfma_f32_16x16x32_bf16 v[86:89], v[148:151], v[206:209], v[86:89]
	v_mfma_f32_16x16x32_bf16 v[70:73], v[144:147], v[210:213], v[70:73]
	v_mfma_f32_16x16x32_bf16 v[70:73], v[148:151], v[214:217], v[70:73]
	v_mfma_f32_16x16x32_bf16 v[114:117], v[152:155], v[180:183], v[114:117]
	v_mfma_f32_16x16x32_bf16 v[114:117], v[156:159], v[184:187], v[114:117]
	v_mfma_f32_16x16x32_bf16 v[98:101], v[152:155], v[188:191], v[98:101]
	v_mfma_f32_16x16x32_bf16 v[98:101], v[156:159], v[192:195], v[98:101]
	v_mfma_f32_16x16x32_bf16 v[82:85], v[152:155], v[202:205], v[82:85]
	v_mfma_f32_16x16x32_bf16 v[82:85], v[156:159], v[206:209], v[82:85]
	v_mfma_f32_16x16x32_bf16 v[66:69], v[152:155], v[210:213], v[66:69]
	v_mfma_f32_16x16x32_bf16 v[66:69], v[156:159], v[214:217], v[66:69]
	v_mfma_f32_16x16x32_bf16 v[126:129], v[160:163], v[180:183], v[126:129]
	v_mfma_f32_16x16x32_bf16 v[126:129], v[164:167], v[184:187], v[126:129]
	v_mfma_f32_16x16x32_bf16 v[110:113], v[160:163], v[188:191], v[110:113]
	v_mfma_f32_16x16x32_bf16 v[110:113], v[164:167], v[192:195], v[110:113]
	v_mfma_f32_16x16x32_bf16 v[94:97], v[160:163], v[202:205], v[94:97]
	v_mfma_f32_16x16x32_bf16 v[94:97], v[164:167], v[206:209], v[94:97]
	v_mfma_f32_16x16x32_bf16 v[78:81], v[160:163], v[210:213], v[78:81]
	v_mfma_f32_16x16x32_bf16 v[78:81], v[164:167], v[214:217], v[78:81]
	v_mfma_f32_16x16x32_bf16 v[122:125], v[168:171], v[180:183], v[122:125]
	v_mfma_f32_16x16x32_bf16 v[122:125], v[172:175], v[184:187], v[122:125]
	v_mfma_f32_16x16x32_bf16 v[106:109], v[168:171], v[188:191], v[106:109]
	v_mfma_f32_16x16x32_bf16 v[106:109], v[172:175], v[192:195], v[106:109]
	v_mfma_f32_16x16x32_bf16 v[90:93], v[168:171], v[202:205], v[90:93]
	v_mfma_f32_16x16x32_bf16 v[90:93], v[172:175], v[206:209], v[90:93]
	v_mfma_f32_16x16x32_bf16 v[74:77], v[168:171], v[210:213], v[74:77]
	v_mfma_f32_16x16x32_bf16 v[74:77], v[172:175], v[214:217], v[74:77]
	s_barrier
; #define PG8_STAGE(bufoff, gbase, voff) do { _Pragma("unroll") for (int _i = 0; _i < 2; ++_i) \
;         __builtin_amdgcn_global_load_lds((const unsigned*)((const char*)(gbase) + (voff)[_i]), (PG8_LAS unsigned*)(lds + (bufoff) + ldsw + _i * 8192), 16, 0, 0); } while (0)
; #define PG8_LDA(dst, b, h) do { _Pragma("unroll") for (int m = 0; m < 4; ++m) _Pragma("unroll") for (int k = 0; k < 2; ++k) dst[m][k] = *(const PG8_LAS bf16x8*)(lds + PG8_SA(b, h) + aoff + m * 2048 + k * 1024); } while (0)
; #define PG8_MMA(ai, bj, At, Bt) do { __builtin_amdgcn_s_setprio(1); _Pragma("unroll") for (int m = 0; m < 4; ++m) _Pragma("unroll") for (int n = 0; n < 2; ++n) _Pragma("unroll") for (int k = 0; k < 2; ++k) \
;         acc[ai][bj][m][n] = __builtin_amdgcn_mfma_f32_16x16x32_bf16(Bt[n][k], At[m][k], acc[ai][bj][m][n], 0, 0, 0); __builtin_amdgcn_s_setprio(0); } while (0)
; #define PG8_WAIT_V(n) asm volatile("s_waitcnt vmcnt(" #n ")" ::: "memory")
; #define PG8_WAIT_L(n) asm volatile("s_waitcnt lgkmcnt(" #n ")" ::: "memory")
; #define PG8_BAR __builtin_amdgcn_s_barrier()
; #define PG8_SCHED __builtin_amdgcn_sched_barrier(0)
; template <class Epi, class Sched, bool ALIGN_EPI = false, bool SP2 = false>
; __device__ __forceinline__ void gemm_phase(PG8_LAS unsigned char* lds, const Gemm g, const Sched& S, const Epi& E) {
;     ...
;             PG8_LDA(At, 1, 1); PG8_STAGE(PG8_SB(1, 0), b3, voffB); PG8_STAGE(PG8_SB(1, 1), b3 + hstep, voffB); PG8_STAGE(PG8_SA(1, 0), a3, voffA);
;             PG8_WAIT_V(8); PG8_WAIT_L(0); PG8_BAR; PG8_MMA(1, 0, At, B0); PG8_MMA(1, 1, At, B1); PG8_BAR; PG8_SCHED;
;     ...
;         if constexpr (ALIGN_EPI) { if (wr == 0) PG8_BAR; }
	s_add_i32 s18, s18, s91
	v_lshl_add_u64 v[218:219], v[218:219], 0, s[30:31]
	s_mov_b32 m0, s18
	ds_read_b128 v[180:183], v178 offset:49152
	ds_read_b128 v[184:187], v178 offset:50176
	ds_read_b128 v[188:191], v178 offset:51200
	ds_read_b128 v[192:195], v178 offset:52224
	ds_read_b128 v[202:205], v178 offset:53248
	ds_read_b128 v[206:209], v178 offset:54272
	ds_read_b128 v[210:213], v178 offset:55296
	ds_read_b128 v[214:217], v178 offset:56320
	global_load_lds_dwordx4 v[218:219], off
	s_add_i32 m0, s18, 0x2000
	s_add_u32 s38, s44, 0x40080
	v_lshl_add_u64 v[218:219], v[220:221], 0, s[30:31]
	s_addc_u32 s39, s45, 0
	s_add_i32 s18, vcc_lo, s91
	global_load_lds_dwordx4 v[218:219], off
	v_lshl_add_u64 v[218:219], s[38:39], 0, v[134:135]
	s_mov_b32 m0, s18
	s_nop 0
	global_load_lds_dwordx4 v[218:219], off
	v_lshl_add_u64 v[218:219], s[38:39], 0, v[130:131]
	s_add_i32 m0, s18, 0x2000
	s_nop 0
	global_load_lds_dwordx4 v[218:219], off
	v_lshl_add_u64 v[218:219], v[222:223], 0, s[30:31]
	s_mov_b32 m0, s7
	s_nop 0
	global_load_lds_dwordx4 v[218:219], off
	v_lshl_add_u64 v[218:219], v[224:225], 0, s[30:31]
	s_mov_b32 m0, s96
	s_nop 0
	global_load_lds_dwordx4 v[218:219], off
	s_waitcnt vmcnt(8)
	s_waitcnt lgkmcnt(0)
	s_barrier
	v_mfma_f32_16x16x32_bf16 v[54:57], v[144:147], v[180:183], v[54:57]
	v_mfma_f32_16x16x32_bf16 v[54:57], v[148:151], v[184:187], v[54:57]
	v_mfma_f32_16x16x32_bf16 v[38:41], v[144:147], v[188:191], v[38:41]
	v_mfma_f32_16x16x32_bf16 v[38:41], v[148:151], v[192:195], v[38:41]
	v_mfma_f32_16x16x32_bf16 v[22:25], v[144:147], v[202:205], v[22:25]
	v_mfma_f32_16x16x32_bf16 v[22:25], v[148:151], v[206:209], v[22:25]
	v_mfma_f32_16x16x32_bf16 v[6:9], v[144:147], v[210:213], v[6:9]
	v_mfma_f32_16x16x32_bf16 v[6:9], v[148:151], v[214:217], v[6:9]
	v_mfma_f32_16x16x32_bf16 v[50:53], v[152:155], v[180:183], v[50:53]
	v_mfma_f32_16x16x32_bf16 v[50:53], v[156:159], v[184:187], v[50:53]
	v_mfma_f32_16x16x32_bf16 v[34:37], v[152:155], v[188:191], v[34:37]
	v_mfma_f32_16x16x32_bf16 v[34:37], v[156:159], v[192:195], v[34:37]
	v_mfma_f32_16x16x32_bf16 v[18:21], v[152:155], v[202:205], v[18:21]
	v_mfma_f32_16x16x32_bf16 v[18:21], v[156:159], v[206:209], v[18:21]
	v_mfma_f32_16x16x32_bf16 v[2:5], v[152:155], v[210:213], v[2:5]
	v_mfma_f32_16x16x32_bf16 v[2:5], v[156:159], v[214:217], v[2:5]
	v_mfma_f32_16x16x32_bf16 v[62:65], v[160:163], v[180:183], v[62:65]
	v_mfma_f32_16x16x32_bf16 v[62:65], v[164:167], v[184:187], v[62:65]
	v_mfma_f32_16x16x32_bf16 v[46:49], v[160:163], v[188:191], v[46:49]
	v_mfma_f32_16x16x32_bf16 v[46:49], v[164:167], v[192:195], v[46:49]
	v_mfma_f32_16x16x32_bf16 v[30:33], v[160:163], v[202:205], v[30:33]
	v_mfma_f32_16x16x32_bf16 v[30:33], v[164:167], v[206:209], v[30:33]
	v_mfma_f32_16x16x32_bf16 v[10:13], v[160:163], v[210:213], v[10:13]
	v_mfma_f32_16x16x32_bf16 v[10:13], v[164:167], v[214:217], v[10:13]
	v_mfma_f32_16x16x32_bf16 v[58:61], v[168:171], v[180:183], v[58:61]
	v_mfma_f32_16x16x32_bf16 v[58:61], v[172:175], v[184:187], v[58:61]
	v_mfma_f32_16x16x32_bf16 v[42:45], v[168:171], v[188:191], v[42:45]
	v_mfma_f32_16x16x32_bf16 v[42:45], v[172:175], v[192:195], v[42:45]
	v_mfma_f32_16x16x32_bf16 v[26:29], v[168:171], v[202:205], v[26:29]
	v_mfma_f32_16x16x32_bf16 v[26:29], v[172:175], v[206:209], v[26:29]
	v_mfma_f32_16x16x32_bf16 v[14:17], v[168:171], v[210:213], v[14:17]
	v_mfma_f32_16x16x32_bf16 v[14:17], v[172:175], v[214:217], v[14:17]
	s_barrier
	s_add_i32 s85, s85, 2
	s_add_u32 s46, s46, 0x100
	s_addc_u32 s47, s47, 0
	s_add_u32 s83, s83, 0x100
	s_addc_u32 s84, s84, 0
	s_cmp_gt_u32 s85, 13
	s_cbranch_scc0 .LBB0_132
	s_and_b64 vcc, exec, s[10:11]
	s_cbranch_vccz .LBB0_135
	s_barrier

; #define PG8_STAGE(bufoff, gbase, voff) do { _Pragma("unroll") for (int _i = 0; _i < 2; ++_i) \
;         __builtin_amdgcn_global_load_lds((const unsigned*)((const char*)(gbase) + (voff)[_i]), (PG8_LAS unsigned*)(lds + (bufoff) + ldsw + _i * 8192), 16, 0, 0); } while (0)
; #define PG8_LDA(dst, b, h) do { _Pragma("unroll") for (int m = 0; m < 4; ++m) _Pragma("unroll") for (int k = 0; k < 2; ++k) dst[m][k] = *(const PG8_LAS bf16x8*)(lds + PG8_SA(b, h) + aoff + m * 2048 + k * 1024); } while (0)
; #define PG8_LDB(dst, b, h) do { _Pragma("unroll") for (int n = 0; n < 2; ++n) _Pragma("unroll") for (int k = 0; k < 2; ++k) dst[n][k] = *(const PG8_LAS bf16x8*)(lds + PG8_SB(b, h) + boff + n * 2048 + k * 1024); } while (0)
; #define PG8_MMA(ai, bj, At, Bt) do { __builtin_amdgcn_s_setprio(1); _Pragma("unroll") for (int m = 0; m < 4; ++m) _Pragma("unroll") for (int n = 0; n < 2; ++n) _Pragma("unroll") for (int k = 0; k < 2; ++k) \
;         acc[ai][bj][m][n] = __builtin_amdgcn_mfma_f32_16x16x32_bf16(Bt[n][k], At[m][k], acc[ai][bj][m][n], 0, 0, 0); __builtin_amdgcn_s_setprio(0); } while (0)
; #define PG8_WAIT_V(n) asm volatile("s_waitcnt vmcnt(" #n ")" ::: "memory")
; #define PG8_WAIT_L(n) asm volatile("s_waitcnt lgkmcnt(" #n ")" ::: "memory")
; #define PG8_BAR __builtin_amdgcn_s_barrier()
; template <class Epi, class Sched, bool ALIGN_EPI = false, bool SP2 = false>
; __device__ __forceinline__ void gemm_phase(PG8_LAS unsigned char* lds, const Gemm g, const Sched& S, const Epi& E) {
;     ...
;             const char* a1 = cA + (size_t)(t + 1) * kstep;
;             const char* a2 = last ? nA : cA + (size_t)(t + 2) * kstep; const char* b2 = last ? nB : cB + (size_t)(t + 2) * kstep;
;             const char* a3 = a2 + kstep; const char* b3 = b2 + kstep;
;             if (last && has_next) S.a_ready(nxt);
;             if constexpr (SP2) {
;             PG8_LDB(B0, 0, 0); PG8_LDB(B1, 0, 1); PG8_SCHED; PG8_LDA(At, 0, 0); PG8_STAGE(PG8_SA(1, 1), a1 + hstep, voffA);
;             PG8_WAIT_V(8); PG8_WAIT_L(0); PG8_BAR; PG8_MMA(0, 0, At, B0); PG8_MMA(0, 1, At, B1); PG8_BAR; PG8_SCHED;
;             PG8_LDA(At, 0, 1); PG8_STAGE(PG8_SB(0, 0), b2, voffB); PG8_STAGE(PG8_SB(0, 1), b2 + hstep, voffB); PG8_STAGE(PG8_SA(0, 0), a2, voffA);
;             PG8_WAIT_V(8); PG8_WAIT_L(0); PG8_BAR; PG8_MMA(1, 0, At, B0); PG8_MMA(1, 1, At, B1); PG8_BAR; PG8_SCHED;
.LBB0_220:
	s_add_u32 s18, s60, 0xfffc0080
	s_addc_u32 s38, s61, -1
	s_add_i32 s39, 0, 0x10000
	s_cmp_eq_u32 s82, 12
	s_cselect_b32 s65, s47, s38
	s_cselect_b32 s64, s78, s18
	v_add_u32_e32 v145, s39, v141
	s_cselect_b32 s57, s49, s81
	s_cselect_b32 s56, s79, s80
	s_add_i32 s18, 0, 0x14000
	ds_read_b128 v[146:149], v145
	ds_read_b128 v[150:153], v145 offset:1024
	ds_read_b128 v[154:157], v145 offset:2048
	ds_read_b128 v[158:161], v145 offset:3072
	v_add_u32_e32 v145, s18, v141
	ds_read_b128 v[162:165], v145
	ds_read_b128 v[166:169], v145 offset:1024
	ds_read_b128 v[170:173], v145 offset:2048
	ds_read_b128 v[174:177], v145 offset:3072
	v_lshl_add_u64 v[194:195], s[60:61], 0, v[136:137]
	s_add_i32 m0, s29, 0xc000
	ds_read_b128 v[178:181], v144
	ds_read_b128 v[182:185], v144 offset:1024
	ds_read_b128 v[186:189], v144 offset:2048
	ds_read_b128 v[190:193], v144 offset:3072
	ds_read_b128 v[202:205], v144 offset:4096
	ds_read_b128 v[206:209], v144 offset:5120
	ds_read_b128 v[210:213], v144 offset:6144
	ds_read_b128 v[214:217], v144 offset:7168
	global_load_lds_dwordx4 v[194:195], off
	v_lshl_add_u64 v[194:195], s[60:61], 0, v[138:139]
	s_add_i32 m0, s29, 0xe000
	s_nop 0
	global_load_lds_dwordx4 v[194:195], off
	s_waitcnt vmcnt(8)
	s_waitcnt lgkmcnt(0)
	s_barrier
	v_mfma_f32_16x16x32_bf16 v[114:117], v[146:149], v[178:181], v[114:117]
	v_mfma_f32_16x16x32_bf16 v[114:117], v[150:153], v[182:185], v[114:117]
	v_mfma_f32_16x16x32_bf16 v[98:101], v[146:149], v[186:189], v[98:101]
	v_mfma_f32_16x16x32_bf16 v[98:101], v[150:153], v[190:193], v[98:101]
	v_mfma_f32_16x16x32_bf16 v[82:85], v[146:149], v[202:205], v[82:85]
	v_mfma_f32_16x16x32_bf16 v[82:85], v[150:153], v[206:209], v[82:85]
	v_mfma_f32_16x16x32_bf16 v[66:69], v[146:149], v[210:213], v[66:69]
	v_mfma_f32_16x16x32_bf16 v[66:69], v[150:153], v[214:217], v[66:69]
	v_mfma_f32_16x16x32_bf16 v[118:121], v[154:157], v[178:181], v[118:121]
	v_mfma_f32_16x16x32_bf16 v[118:121], v[158:161], v[182:185], v[118:121]
	v_mfma_f32_16x16x32_bf16 v[102:105], v[154:157], v[186:189], v[102:105]
	v_mfma_f32_16x16x32_bf16 v[102:105], v[158:161], v[190:193], v[102:105]
	v_mfma_f32_16x16x32_bf16 v[86:89], v[154:157], v[202:205], v[86:89]
	v_mfma_f32_16x16x32_bf16 v[86:89], v[158:161], v[206:209], v[86:89]
	v_mfma_f32_16x16x32_bf16 v[70:73], v[154:157], v[210:213], v[70:73]
	v_mfma_f32_16x16x32_bf16 v[70:73], v[158:161], v[214:217], v[70:73]
	v_mfma_f32_16x16x32_bf16 v[122:125], v[162:165], v[178:181], v[122:125]
	v_mfma_f32_16x16x32_bf16 v[122:125], v[166:169], v[182:185], v[122:125]
	v_mfma_f32_16x16x32_bf16 v[106:109], v[162:165], v[186:189], v[106:109]
	v_mfma_f32_16x16x32_bf16 v[106:109], v[166:169], v[190:193], v[106:109]
	v_mfma_f32_16x16x32_bf16 v[90:93], v[162:165], v[202:205], v[90:93]
	v_mfma_f32_16x16x32_bf16 v[90:93], v[166:169], v[206:209], v[90:93]
	v_mfma_f32_16x16x32_bf16 v[74:77], v[162:165], v[210:213], v[74:77]
	v_mfma_f32_16x16x32_bf16 v[74:77], v[166:169], v[214:217], v[74:77]
	v_mfma_f32_16x16x32_bf16 v[126:129], v[170:173], v[178:181], v[126:129]
	v_mfma_f32_16x16x32_bf16 v[126:129], v[174:177], v[182:185], v[126:129]
	v_mfma_f32_16x16x32_bf16 v[110:113], v[170:173], v[186:189], v[110:113]
	v_mfma_f32_16x16x32_bf16 v[110:113], v[174:177], v[190:193], v[110:113]
	v_mfma_f32_16x16x32_bf16 v[94:97], v[170:173], v[202:205], v[94:97]
	v_mfma_f32_16x16x32_bf16 v[94:97], v[174:177], v[206:209], v[94:97]
	v_mfma_f32_16x16x32_bf16 v[78:81], v[170:173], v[210:213], v[78:81]
	v_mfma_f32_16x16x32_bf16 v[78:81], v[174:177], v[214:217], v[78:81]
	s_barrier
	s_add_i32 s38, s39, s27
	v_lshl_add_u64 v[194:195], s[56:57], 0, v[0:1]
	s_mov_b32 m0, s38
	ds_read_b128 v[178:181], v144 offset:16384
	ds_read_b128 v[182:185], v144 offset:17408
	ds_read_b128 v[186:189], v144 offset:18432
	ds_read_b128 v[190:193], v144 offset:19456
	ds_read_b128 v[202:205], v144 offset:20480
	ds_read_b128 v[206:209], v144 offset:21504
	ds_read_b128 v[210:213], v144 offset:22528
	ds_read_b128 v[214:217], v144 offset:23552
	global_load_lds_dwordx4 v[194:195], off
	s_add_i32 m0, s38, 0x2000
	s_add_u32 s38, s56, 0x40000
	v_lshl_add_u64 v[218:219], s[56:57], 0, v[130:131]
	s_addc_u32 s39, s57, 0
	s_add_i32 s18, s18, s27
	global_load_lds_dwordx4 v[218:219], off
	v_lshl_add_u64 v[220:221], s[38:39], 0, v[0:1]
	s_mov_b32 m0, s18
	v_lshl_add_u64 v[222:223], s[64:65], 0, v[132:133]
	global_load_lds_dwordx4 v[220:221], off
	v_lshl_add_u64 v[220:221], s[38:39], 0, v[130:131]
	s_add_i32 m0, s18, 0x2000
	s_nop 0
	global_load_lds_dwordx4 v[220:221], off
	v_lshl_add_u64 v[220:221], s[64:65], 0, v[134:135]
	s_mov_b32 m0, s29
	s_nop 0
	global_load_lds_dwordx4 v[220:221], off
	s_mov_b32 m0, s33
	s_nop 0
	global_load_lds_dwordx4 v[222:223], off
	s_waitcnt vmcnt(8)
	s_waitcnt lgkmcnt(0)
	s_barrier
; #define PG8_STAGE(bufoff, gbase, voff) do { _Pragma("unroll") for (int _i = 0; _i < 2; ++_i) \
;         __builtin_amdgcn_global_load_lds((const unsigned*)((const char*)(gbase) + (voff)[_i]), (PG8_LAS unsigned*)(lds + (bufoff) + ldsw + _i * 8192), 16, 0, 0); } while (0)
; #define PG8_LDA(dst, b, h) do { _Pragma("unroll") for (int m = 0; m < 4; ++m) _Pragma("unroll") for (int k = 0; k < 2; ++k) dst[m][k] = *(const PG8_LAS bf16x8*)(lds + PG8_SA(b, h) + aoff + m * 2048 + k * 1024); } while (0)
; #define PG8_LDB(dst, b, h) do { _Pragma("unroll") for (int n = 0; n < 2; ++n) _Pragma("unroll") for (int k = 0; k < 2; ++k) dst[n][k] = *(const PG8_LAS bf16x8*)(lds + PG8_SB(b, h) + boff + n * 2048 + k * 1024); } while (0)
; #define PG8_MMA(ai, bj, At, Bt) do { __builtin_amdgcn_s_setprio(1); _Pragma("unroll") for (int m = 0; m < 4; ++m) _Pragma("unroll") for (int n = 0; n < 2; ++n) _Pragma("unroll") for (int k = 0; k < 2; ++k) \
;         acc[ai][bj][m][n] = __builtin_amdgcn_mfma_f32_16x16x32_bf16(Bt[n][k], At[m][k], acc[ai][bj][m][n], 0, 0, 0); __builtin_amdgcn_s_setprio(0); } while (0)
; #define PG8_WAIT_V(n) asm volatile("s_waitcnt vmcnt(" #n ")" ::: "memory")
; #define PG8_WAIT_L(n) asm volatile("s_waitcnt lgkmcnt(" #n ")" ::: "memory")
; #define PG8_BAR __builtin_amdgcn_s_barrier()
; #define PG8_SCHED __builtin_amdgcn_sched_barrier(0)
; template <class Epi, class Sched, bool ALIGN_EPI = false, bool SP2 = false>
; __device__ __forceinline__ void gemm_phase(PG8_LAS unsigned char* lds, const Gemm g, const Sched& S, const Epi& E) {
;     ...
;             PG8_WAIT_V(8); PG8_WAIT_L(0); PG8_BAR; PG8_MMA(1, 0, At, B0); PG8_MMA(1, 1, At, B1); PG8_BAR; PG8_SCHED;
;             PG8_LDB(B0, 1, 0); PG8_LDB(B1, 1, 1); PG8_SCHED; PG8_LDA(At, 1, 0); PG8_STAGE(PG8_SA(0, 1), a2 + hstep, voffA);
;             PG8_WAIT_V(8); PG8_WAIT_L(0); PG8_BAR; PG8_MMA(0, 0, At, B0); PG8_MMA(0, 1, At, B1); PG8_BAR; PG8_SCHED;
	v_mfma_f32_16x16x32_bf16 v[50:53], v[146:149], v[178:181], v[50:53]
	v_mfma_f32_16x16x32_bf16 v[50:53], v[150:153], v[182:185], v[50:53]
	v_mfma_f32_16x16x32_bf16 v[34:37], v[146:149], v[186:189], v[34:37]
	v_mfma_f32_16x16x32_bf16 v[34:37], v[150:153], v[190:193], v[34:37]
	v_mfma_f32_16x16x32_bf16 v[18:21], v[146:149], v[202:205], v[18:21]
	v_mfma_f32_16x16x32_bf16 v[18:21], v[150:153], v[206:209], v[18:21]
	v_mfma_f32_16x16x32_bf16 v[2:5], v[146:149], v[210:213], v[2:5]
	v_mfma_f32_16x16x32_bf16 v[2:5], v[150:153], v[214:217], v[2:5]
	v_mfma_f32_16x16x32_bf16 v[54:57], v[154:157], v[178:181], v[54:57]
	v_mfma_f32_16x16x32_bf16 v[54:57], v[158:161], v[182:185], v[54:57]
	v_mfma_f32_16x16x32_bf16 v[38:41], v[154:157], v[186:189], v[38:41]
	v_mfma_f32_16x16x32_bf16 v[38:41], v[158:161], v[190:193], v[38:41]
	v_mfma_f32_16x16x32_bf16 v[22:25], v[154:157], v[202:205], v[22:25]
	v_mfma_f32_16x16x32_bf16 v[22:25], v[158:161], v[206:209], v[22:25]
	v_mfma_f32_16x16x32_bf16 v[6:9], v[154:157], v[210:213], v[6:9]
	v_mfma_f32_16x16x32_bf16 v[6:9], v[158:161], v[214:217], v[6:9]
	v_mfma_f32_16x16x32_bf16 v[58:61], v[162:165], v[178:181], v[58:61]
	v_mfma_f32_16x16x32_bf16 v[58:61], v[166:169], v[182:185], v[58:61]
	v_mfma_f32_16x16x32_bf16 v[42:45], v[162:165], v[186:189], v[42:45]
	v_mfma_f32_16x16x32_bf16 v[42:45], v[166:169], v[190:193], v[42:45]
	v_mfma_f32_16x16x32_bf16 v[26:29], v[162:165], v[202:205], v[26:29]
	v_mfma_f32_16x16x32_bf16 v[26:29], v[166:169], v[206:209], v[26:29]
	v_mfma_f32_16x16x32_bf16 v[10:13], v[162:165], v[210:213], v[10:13]
	v_mfma_f32_16x16x32_bf16 v[10:13], v[166:169], v[214:217], v[10:13]
	v_mfma_f32_16x16x32_bf16 v[62:65], v[170:173], v[178:181], v[62:65]
	v_mfma_f32_16x16x32_bf16 v[62:65], v[174:177], v[182:185], v[62:65]
	v_mfma_f32_16x16x32_bf16 v[46:49], v[170:173], v[186:189], v[46:49]
	v_mfma_f32_16x16x32_bf16 v[46:49], v[174:177], v[190:193], v[46:49]
	v_mfma_f32_16x16x32_bf16 v[30:33], v[170:173], v[202:205], v[30:33]
	v_mfma_f32_16x16x32_bf16 v[30:33], v[174:177], v[206:209], v[30:33]
	v_mfma_f32_16x16x32_bf16 v[14:17], v[170:173], v[210:213], v[14:17]
	v_mfma_f32_16x16x32_bf16 v[14:17], v[174:177], v[214:217], v[14:17]
	s_barrier
	s_add_i32 s18, 0, 0x18000
	v_add_u32_e32 v145, s18, v141
	s_add_i32 s83, 0, 0x1c000
	ds_read_b128 v[146:149], v145
	ds_read_b128 v[150:153], v145 offset:1024
	ds_read_b128 v[154:157], v145 offset:2048
	ds_read_b128 v[158:161], v145 offset:3072
	v_add_u32_e32 v145, s83, v141
	ds_read_b128 v[162:165], v145
	ds_read_b128 v[166:169], v145 offset:1024
	ds_read_b128 v[170:173], v145 offset:2048
	ds_read_b128 v[174:177], v145 offset:3072
	s_add_u32 s38, s64, 0x40000
	s_addc_u32 s39, s65, 0
	s_mov_b32 m0, s58
	v_lshl_add_u64 v[224:225], s[38:39], 0, v[134:135]
	ds_read_b128 v[178:181], v144 offset:32768
	ds_read_b128 v[182:185], v144 offset:33792
	ds_read_b128 v[186:189], v144 offset:34816
	ds_read_b128 v[190:193], v144 offset:35840
	ds_read_b128 v[202:205], v144 offset:36864
	ds_read_b128 v[206:209], v144 offset:37888
	ds_read_b128 v[210:213], v144 offset:38912
	ds_read_b128 v[214:217], v144 offset:39936
	global_load_lds_dwordx4 v[224:225], off
	v_lshl_add_u64 v[224:225], s[38:39], 0, v[132:133]
	s_mov_b32 m0, s69
	s_nop 0
	global_load_lds_dwordx4 v[224:225], off
	s_waitcnt vmcnt(8)
	s_waitcnt lgkmcnt(0)
	s_barrier
	v_mfma_f32_16x16x32_bf16 v[114:117], v[146:149], v[178:181], v[114:117]
	v_mfma_f32_16x16x32_bf16 v[114:117], v[150:153], v[182:185], v[114:117]
	v_mfma_f32_16x16x32_bf16 v[98:101], v[146:149], v[186:189], v[98:101]
	v_mfma_f32_16x16x32_bf16 v[98:101], v[150:153], v[190:193], v[98:101]
	v_mfma_f32_16x16x32_bf16 v[82:85], v[146:149], v[202:205], v[82:85]
	v_mfma_f32_16x16x32_bf16 v[82:85], v[150:153], v[206:209], v[82:85]
	v_mfma_f32_16x16x32_bf16 v[66:69], v[146:149], v[210:213], v[66:69]
	v_mfma_f32_16x16x32_bf16 v[66:69], v[150:153], v[214:217], v[66:69]
	v_mfma_f32_16x16x32_bf16 v[118:121], v[154:157], v[178:181], v[118:121]
	v_mfma_f32_16x16x32_bf16 v[118:121], v[158:161], v[182:185], v[118:121]
	v_mfma_f32_16x16x32_bf16 v[102:105], v[154:157], v[186:189], v[102:105]
	v_mfma_f32_16x16x32_bf16 v[102:105], v[158:161], v[190:193], v[102:105]
	v_mfma_f32_16x16x32_bf16 v[86:89], v[154:157], v[202:205], v[86:89]
	v_mfma_f32_16x16x32_bf16 v[86:89], v[158:161], v[206:209], v[86:89]
	v_mfma_f32_16x16x32_bf16 v[70:73], v[154:157], v[210:213], v[70:73]
	v_mfma_f32_16x16x32_bf16 v[70:73], v[158:161], v[214:217], v[70:73]
	v_mfma_f32_16x16x32_bf16 v[122:125], v[162:165], v[178:181], v[122:125]
	v_mfma_f32_16x16x32_bf16 v[122:125], v[166:169], v[182:185], v[122:125]
	v_mfma_f32_16x16x32_bf16 v[106:109], v[162:165], v[186:189], v[106:109]
	v_mfma_f32_16x16x32_bf16 v[106:109], v[166:169], v[190:193], v[106:109]
	v_mfma_f32_16x16x32_bf16 v[90:93], v[162:165], v[202:205], v[90:93]
	v_mfma_f32_16x16x32_bf16 v[90:93], v[166:169], v[206:209], v[90:93]
	v_mfma_f32_16x16x32_bf16 v[74:77], v[162:165], v[210:213], v[74:77]
	v_mfma_f32_16x16x32_bf16 v[74:77], v[166:169], v[214:217], v[74:77]
	v_mfma_f32_16x16x32_bf16 v[126:129], v[170:173], v[178:181], v[126:129]
	v_mfma_f32_16x16x32_bf16 v[126:129], v[174:177], v[182:185], v[126:129]
	v_mfma_f32_16x16x32_bf16 v[110:113], v[170:173], v[186:189], v[110:113]
	v_mfma_f32_16x16x32_bf16 v[110:113], v[174:177], v[190:193], v[110:113]
	v_mfma_f32_16x16x32_bf16 v[94:97], v[170:173], v[202:205], v[94:97]
	v_mfma_f32_16x16x32_bf16 v[94:97], v[174:177], v[206:209], v[94:97]
	v_mfma_f32_16x16x32_bf16 v[78:81], v[170:173], v[210:213], v[78:81]
	v_mfma_f32_16x16x32_bf16 v[78:81], v[174:177], v[214:217], v[78:81]
	s_barrier
; #define PG8_STAGE(bufoff, gbase, voff) do { _Pragma("unroll") for (int _i = 0; _i < 2; ++_i) \
;         __builtin_amdgcn_global_load_lds((const unsigned*)((const char*)(gbase) + (voff)[_i]), (PG8_LAS unsigned*)(lds + (bufoff) + ldsw + _i * 8192), 16, 0, 0); } while (0)
; #define PG8_LDA(dst, b, h) do { _Pragma("unroll") for (int m = 0; m < 4; ++m) _Pragma("unroll") for (int k = 0; k < 2; ++k) dst[m][k] = *(const PG8_LAS bf16x8*)(lds + PG8_SA(b, h) + aoff + m * 2048 + k * 1024); } while (0)
; #define PG8_MMA(ai, bj, At, Bt) do { __builtin_amdgcn_s_setprio(1); _Pragma("unroll") for (int m = 0; m < 4; ++m) _Pragma("unroll") for (int n = 0; n < 2; ++n) _Pragma("unroll") for (int k = 0; k < 2; ++k) \
;         acc[ai][bj][m][n] = __builtin_amdgcn_mfma_f32_16x16x32_bf16(Bt[n][k], At[m][k], acc[ai][bj][m][n], 0, 0, 0); __builtin_amdgcn_s_setprio(0); } while (0)
; #define PG8_WAIT_V(n) asm volatile("s_waitcnt vmcnt(" #n ")" ::: "memory")
; #define PG8_WAIT_L(n) asm volatile("s_waitcnt lgkmcnt(" #n ")" ::: "memory")
; #define PG8_BAR __builtin_amdgcn_s_barrier()
; #define PG8_SCHED __builtin_amdgcn_sched_barrier(0)
; template <class Epi, class Sched, bool ALIGN_EPI = false, bool SP2 = false>
; __device__ __forceinline__ void gemm_phase(PG8_LAS unsigned char* lds, const Gemm g, const Sched& S, const Epi& E) {
;     ...
;             PG8_LDA(At, 1, 1); PG8_STAGE(PG8_SB(1, 0), b3, voffB); PG8_STAGE(PG8_SB(1, 1), b3 + hstep, voffB); PG8_STAGE(PG8_SA(1, 0), a3, voffA);
;             PG8_WAIT_V(8); PG8_WAIT_L(0); PG8_BAR; PG8_MMA(1, 0, At, B0); PG8_MMA(1, 1, At, B1); PG8_BAR; PG8_SCHED;
;     ...
;         if constexpr (ALIGN_EPI) { if (wr == 0) PG8_BAR; }
	s_add_i32 s18, s18, s27
	v_lshl_add_u64 v[194:195], v[194:195], 0, s[30:31]
	s_mov_b32 m0, s18
	ds_read_b128 v[178:181], v144 offset:49152
	ds_read_b128 v[182:185], v144 offset:50176
	ds_read_b128 v[186:189], v144 offset:51200
	ds_read_b128 v[190:193], v144 offset:52224
	ds_read_b128 v[202:205], v144 offset:53248
	ds_read_b128 v[206:209], v144 offset:54272
	ds_read_b128 v[210:213], v144 offset:55296
	ds_read_b128 v[214:217], v144 offset:56320
	global_load_lds_dwordx4 v[194:195], off
	s_add_i32 m0, s18, 0x2000
	s_add_u32 s38, s56, 0x40080
	v_lshl_add_u64 v[194:195], v[218:219], 0, s[30:31]
	s_addc_u32 s39, s57, 0
	s_add_i32 s18, s83, s27
	global_load_lds_dwordx4 v[194:195], off
	v_lshl_add_u64 v[194:195], s[38:39], 0, v[0:1]
	s_mov_b32 m0, s18
	s_nop 0
	global_load_lds_dwordx4 v[194:195], off
	v_lshl_add_u64 v[194:195], s[38:39], 0, v[130:131]
	s_add_i32 m0, s18, 0x2000
	s_nop 0
	global_load_lds_dwordx4 v[194:195], off
	v_lshl_add_u64 v[194:195], v[220:221], 0, s[30:31]
	s_mov_b32 m0, s71
	s_nop 0
	global_load_lds_dwordx4 v[194:195], off
	v_lshl_add_u64 v[194:195], v[222:223], 0, s[30:31]
	s_mov_b32 m0, s72
	s_nop 0
	global_load_lds_dwordx4 v[194:195], off
	s_waitcnt vmcnt(8)
	s_waitcnt lgkmcnt(0)
	s_barrier
	v_mfma_f32_16x16x32_bf16 v[50:53], v[146:149], v[178:181], v[50:53]
	v_mfma_f32_16x16x32_bf16 v[50:53], v[150:153], v[182:185], v[50:53]
	v_mfma_f32_16x16x32_bf16 v[34:37], v[146:149], v[186:189], v[34:37]
	v_mfma_f32_16x16x32_bf16 v[34:37], v[150:153], v[190:193], v[34:37]
	v_mfma_f32_16x16x32_bf16 v[18:21], v[146:149], v[202:205], v[18:21]
	v_mfma_f32_16x16x32_bf16 v[18:21], v[150:153], v[206:209], v[18:21]
	v_mfma_f32_16x16x32_bf16 v[2:5], v[146:149], v[210:213], v[2:5]
	v_mfma_f32_16x16x32_bf16 v[2:5], v[150:153], v[214:217], v[2:5]
	v_mfma_f32_16x16x32_bf16 v[54:57], v[154:157], v[178:181], v[54:57]
	v_mfma_f32_16x16x32_bf16 v[54:57], v[158:161], v[182:185], v[54:57]
	v_mfma_f32_16x16x32_bf16 v[38:41], v[154:157], v[186:189], v[38:41]
	v_mfma_f32_16x16x32_bf16 v[38:41], v[158:161], v[190:193], v[38:41]
	v_mfma_f32_16x16x32_bf16 v[22:25], v[154:157], v[202:205], v[22:25]
	v_mfma_f32_16x16x32_bf16 v[22:25], v[158:161], v[206:209], v[22:25]
	v_mfma_f32_16x16x32_bf16 v[6:9], v[154:157], v[210:213], v[6:9]
	v_mfma_f32_16x16x32_bf16 v[6:9], v[158:161], v[214:217], v[6:9]
	v_mfma_f32_16x16x32_bf16 v[58:61], v[162:165], v[178:181], v[58:61]
	v_mfma_f32_16x16x32_bf16 v[58:61], v[166:169], v[182:185], v[58:61]
	v_mfma_f32_16x16x32_bf16 v[42:45], v[162:165], v[186:189], v[42:45]
	v_mfma_f32_16x16x32_bf16 v[42:45], v[166:169], v[190:193], v[42:45]
	v_mfma_f32_16x16x32_bf16 v[26:29], v[162:165], v[202:205], v[26:29]
	v_mfma_f32_16x16x32_bf16 v[26:29], v[166:169], v[206:209], v[26:29]
	v_mfma_f32_16x16x32_bf16 v[10:13], v[162:165], v[210:213], v[10:13]
	v_mfma_f32_16x16x32_bf16 v[10:13], v[166:169], v[214:217], v[10:13]
	v_mfma_f32_16x16x32_bf16 v[62:65], v[170:173], v[178:181], v[62:65]
	v_mfma_f32_16x16x32_bf16 v[62:65], v[174:177], v[182:185], v[62:65]
	v_mfma_f32_16x16x32_bf16 v[46:49], v[170:173], v[186:189], v[46:49]
	v_mfma_f32_16x16x32_bf16 v[46:49], v[174:177], v[190:193], v[46:49]
	v_mfma_f32_16x16x32_bf16 v[30:33], v[170:173], v[202:205], v[30:33]
	v_mfma_f32_16x16x32_bf16 v[30:33], v[174:177], v[206:209], v[30:33]
	v_mfma_f32_16x16x32_bf16 v[14:17], v[170:173], v[210:213], v[14:17]
	v_mfma_f32_16x16x32_bf16 v[14:17], v[174:177], v[214:217], v[14:17]
	s_barrier
	s_add_i32 s82, s82, 2
	s_add_u32 s60, s60, 0x100
	s_addc_u32 s61, s61, 0
	s_add_u32 s80, s80, 0x100
	s_addc_u32 s81, s81, 0
	s_cmp_gt_u32 s82, 13
	s_cbranch_scc0 .LBB0_220
	s_and_b64 vcc, exec, s[44:45]
	s_cbranch_vccz .LBB0_223
	s_barrier

; #define PG8_STAGE(bufoff, gbase, voff) do { _Pragma("unroll") for (int _i = 0; _i < 2; ++_i) \
;         __builtin_amdgcn_global_load_lds((const unsigned*)((const char*)(gbase) + (voff)[_i]), (PG8_LAS unsigned*)(lds + (bufoff) + ldsw + _i * 8192), 16, 0, 0); } while (0)
; #define PG8_LDA(dst, b, h) do { _Pragma("unroll") for (int m = 0; m < 4; ++m) _Pragma("unroll") for (int k = 0; k < 2; ++k) dst[m][k] = *(const PG8_LAS bf16x8*)(lds + PG8_SA(b, h) + aoff + m * 2048 + k * 1024); } while (0)
; #define PG8_LDB(dst, b, h) do { _Pragma("unroll") for (int n = 0; n < 2; ++n) _Pragma("unroll") for (int k = 0; k < 2; ++k) dst[n][k] = *(const PG8_LAS bf16x8*)(lds + PG8_SB(b, h) + boff + n * 2048 + k * 1024); } while (0)
; #define PG8_MMA(ai, bj, At, Bt) do { __builtin_amdgcn_s_setprio(1); _Pragma("unroll") for (int m = 0; m < 4; ++m) _Pragma("unroll") for (int n = 0; n < 2; ++n) _Pragma("unroll") for (int k = 0; k < 2; ++k) \
;         acc[ai][bj][m][n] = __builtin_amdgcn_mfma_f32_16x16x32_bf16(Bt[n][k], At[m][k], acc[ai][bj][m][n], 0, 0, 0); __builtin_amdgcn_s_setprio(0); } while (0)
; #define PG8_WAIT_V(n) asm volatile("s_waitcnt vmcnt(" #n ")" ::: "memory")
; #define PG8_WAIT_L(n) asm volatile("s_waitcnt lgkmcnt(" #n ")" ::: "memory")
; #define PG8_BAR __builtin_amdgcn_s_barrier()
; template <class Epi, class Sched, bool ALIGN_EPI = false, bool SP2 = false>
; __device__ __forceinline__ void gemm_phase(PG8_LAS unsigned char* lds, const Gemm g, const Sched& S, const Epi& E) {
;     ...
;             const char* a1 = cA + (size_t)(t + 1) * kstep;
;             const char* a2 = last ? nA : cA + (size_t)(t + 2) * kstep; const char* b2 = last ? nB : cB + (size_t)(t + 2) * kstep;
;             const char* a3 = a2 + kstep; const char* b3 = b2 + kstep;
;             if (last && has_next) S.a_ready(nxt);
;             if constexpr (SP2) {
;             PG8_LDB(B0, 0, 0); PG8_LDB(B1, 0, 1); PG8_SCHED; PG8_LDA(At, 0, 0); PG8_STAGE(PG8_SA(1, 1), a1 + hstep, voffA);
;             PG8_WAIT_V(8); PG8_WAIT_L(0); PG8_BAR; PG8_MMA(0, 0, At, B0); PG8_MMA(0, 1, At, B1); PG8_BAR; PG8_SCHED;
;             PG8_LDA(At, 0, 1); PG8_STAGE(PG8_SB(0, 0), b2, voffB); PG8_STAGE(PG8_SB(0, 1), b2 + hstep, voffB); PG8_STAGE(PG8_SA(0, 0), a2, voffA);
;             PG8_WAIT_V(8); PG8_WAIT_L(0); PG8_BAR; PG8_MMA(1, 0, At, B0); PG8_MMA(1, 1, At, B1); PG8_BAR; PG8_SCHED;
.LBB0_274:
	s_add_i32 vcc_lo, s46, 2
	s_add_u32 s38, s48, 0x80
	s_addc_u32 s39, s49, 0
	s_add_i32 vcc_hi, 0, 0x10000
	s_cmp_eq_u32 s99, s46
	s_cselect_b32 s47, s81, s39
	s_cselect_b32 s46, s80, s38
	s_cselect_b32 s39, s83, s51
	s_cselect_b32 s38, s82, s50
	s_add_i32 s18, 0, 0x14000
	v_add_u32_e32 v142, vcc_hi, v245
	v_add_u32_e32 v158, s18, v245
	ds_read_b128 v[110:113], v142
	ds_read_b128 v[118:121], v142 offset:1024
	ds_read_b128 v[138:141], v142 offset:2048
	ds_read_b128 v[142:145], v142 offset:3072
	ds_read_b128 v[146:149], v158
	ds_read_b128 v[150:153], v158 offset:1024
	ds_read_b128 v[154:157], v158 offset:2048
	ds_read_b128 v[158:161], v158 offset:3072
	v_lshl_add_u64 v[210:211], s[48:49], 0, v[206:207]
	s_add_i32 m0, s92, 0xc000
	ds_read_b128 v[162:165], v247
	ds_read_b128 v[166:169], v247 offset:1024
	ds_read_b128 v[170:173], v247 offset:2048
	ds_read_b128 v[174:177], v247 offset:3072
	ds_read_b128 v[178:181], v247 offset:4096
	ds_read_b128 v[182:185], v247 offset:5120
	ds_read_b128 v[186:189], v247 offset:6144
	ds_read_b128 v[190:193], v247 offset:7168
	global_load_lds_dwordx4 v[210:211], off
	v_lshl_add_u64 v[210:211], s[48:49], 0, v[208:209]
	s_add_i32 m0, s92, 0xe000
	s_nop 0
	global_load_lds_dwordx4 v[210:211], off
	s_waitcnt vmcnt(8)
	s_waitcnt lgkmcnt(0)
	s_barrier
	v_mfma_f32_16x16x32_bf16 v[130:133], v[110:113], v[162:165], v[130:133]
	v_mfma_f32_16x16x32_bf16 v[130:133], v[118:121], v[166:169], v[130:133]
	v_mfma_f32_16x16x32_bf16 v[114:117], v[110:113], v[170:173], v[114:117]
	v_mfma_f32_16x16x32_bf16 v[114:117], v[118:121], v[174:177], v[114:117]
	v_mfma_f32_16x16x32_bf16 v[94:97], v[110:113], v[178:181], v[94:97]
	v_mfma_f32_16x16x32_bf16 v[94:97], v[118:121], v[182:185], v[94:97]
	v_mfma_f32_16x16x32_bf16 v[78:81], v[110:113], v[186:189], v[78:81]
	v_mfma_f32_16x16x32_bf16 v[78:81], v[118:121], v[190:193], v[78:81]
	v_mfma_f32_16x16x32_bf16 v[134:137], v[138:141], v[162:165], v[134:137]
	v_mfma_f32_16x16x32_bf16 v[134:137], v[142:145], v[166:169], v[134:137]
	v_mfma_f32_16x16x32_bf16 v[106:109], v[138:141], v[170:173], v[106:109]
	v_mfma_f32_16x16x32_bf16 v[106:109], v[142:145], v[174:177], v[106:109]
	v_mfma_f32_16x16x32_bf16 v[90:93], v[138:141], v[178:181], v[90:93]
	v_mfma_f32_16x16x32_bf16 v[90:93], v[142:145], v[182:185], v[90:93]
	v_mfma_f32_16x16x32_bf16 v[74:77], v[138:141], v[186:189], v[74:77]
	v_mfma_f32_16x16x32_bf16 v[74:77], v[142:145], v[190:193], v[74:77]
	v_mfma_f32_16x16x32_bf16 v[126:129], v[146:149], v[162:165], v[126:129]
	v_mfma_f32_16x16x32_bf16 v[126:129], v[150:153], v[166:169], v[126:129]
	v_mfma_f32_16x16x32_bf16 v[102:105], v[146:149], v[170:173], v[102:105]
	v_mfma_f32_16x16x32_bf16 v[102:105], v[150:153], v[174:177], v[102:105]
	v_mfma_f32_16x16x32_bf16 v[86:89], v[146:149], v[178:181], v[86:89]
	v_mfma_f32_16x16x32_bf16 v[86:89], v[150:153], v[182:185], v[86:89]
	v_mfma_f32_16x16x32_bf16 v[70:73], v[146:149], v[186:189], v[70:73]
	v_mfma_f32_16x16x32_bf16 v[70:73], v[150:153], v[190:193], v[70:73]
	v_mfma_f32_16x16x32_bf16 v[122:125], v[154:157], v[162:165], v[122:125]
	v_mfma_f32_16x16x32_bf16 v[122:125], v[158:161], v[166:169], v[122:125]
	v_mfma_f32_16x16x32_bf16 v[98:101], v[154:157], v[170:173], v[98:101]
	v_mfma_f32_16x16x32_bf16 v[98:101], v[158:161], v[174:177], v[98:101]
	v_mfma_f32_16x16x32_bf16 v[82:85], v[154:157], v[178:181], v[82:85]
	v_mfma_f32_16x16x32_bf16 v[82:85], v[158:161], v[182:185], v[82:85]
	v_mfma_f32_16x16x32_bf16 v[66:69], v[154:157], v[186:189], v[66:69]
	v_mfma_f32_16x16x32_bf16 v[66:69], v[158:161], v[190:193], v[66:69]
	s_barrier
	s_add_i32 vcc_hi, vcc_hi, s6
	v_lshl_add_u64 v[210:211], s[38:39], 0, v[0:1]
	s_mov_b32 m0, vcc_hi
	ds_read_b128 v[162:165], v247 offset:16384
	ds_read_b128 v[166:169], v247 offset:17408
	ds_read_b128 v[170:173], v247 offset:18432
	ds_read_b128 v[174:177], v247 offset:19456
	ds_read_b128 v[178:181], v247 offset:20480
	ds_read_b128 v[182:185], v247 offset:21504
	ds_read_b128 v[186:189], v247 offset:22528
	ds_read_b128 v[190:193], v247 offset:23552
	global_load_lds_dwordx4 v[210:211], off
	s_add_i32 m0, vcc_hi, 0x2000
	v_lshl_add_u64 v[212:213], s[38:39], 0, v[204:205]
	s_add_u32 s38, s38, s58
	s_addc_u32 s39, s39, 0
	s_add_i32 s18, s18, s6
	global_load_lds_dwordx4 v[212:213], off
	v_lshl_add_u64 v[214:215], s[38:39], 0, v[0:1]
	s_mov_b32 m0, s18
	v_lshl_add_u64 v[216:217], s[38:39], 0, v[204:205]
	global_load_lds_dwordx4 v[214:215], off
	s_add_i32 m0, s18, 0x2000
	v_lshl_add_u64 v[218:219], s[46:47], 0, v[194:195]
	global_load_lds_dwordx4 v[216:217], off
	s_mov_b32 m0, s92
	v_lshl_add_u64 v[220:221], s[46:47], 0, v[202:203]
	global_load_lds_dwordx4 v[218:219], off
	s_mov_b32 m0, s93
	s_nop 0
	global_load_lds_dwordx4 v[220:221], off
	s_waitcnt vmcnt(8)
	s_waitcnt lgkmcnt(0)
	s_barrier
; #define PG8_STAGE(bufoff, gbase, voff) do { _Pragma("unroll") for (int _i = 0; _i < 2; ++_i) \
;         __builtin_amdgcn_global_load_lds((const unsigned*)((const char*)(gbase) + (voff)[_i]), (PG8_LAS unsigned*)(lds + (bufoff) + ldsw + _i * 8192), 16, 0, 0); } while (0)
; #define PG8_LDA(dst, b, h) do { _Pragma("unroll") for (int m = 0; m < 4; ++m) _Pragma("unroll") for (int k = 0; k < 2; ++k) dst[m][k] = *(const PG8_LAS bf16x8*)(lds + PG8_SA(b, h) + aoff + m * 2048 + k * 1024); } while (0)
; #define PG8_LDB(dst, b, h) do { _Pragma("unroll") for (int n = 0; n < 2; ++n) _Pragma("unroll") for (int k = 0; k < 2; ++k) dst[n][k] = *(const PG8_LAS bf16x8*)(lds + PG8_SB(b, h) + boff + n * 2048 + k * 1024); } while (0)
; #define PG8_MMA(ai, bj, At, Bt) do { __builtin_amdgcn_s_setprio(1); _Pragma("unroll") for (int m = 0; m < 4; ++m) _Pragma("unroll") for (int n = 0; n < 2; ++n) _Pragma("unroll") for (int k = 0; k < 2; ++k) \
;         acc[ai][bj][m][n] = __builtin_amdgcn_mfma_f32_16x16x32_bf16(Bt[n][k], At[m][k], acc[ai][bj][m][n], 0, 0, 0); __builtin_amdgcn_s_setprio(0); } while (0)
; #define PG8_WAIT_V(n) asm volatile("s_waitcnt vmcnt(" #n ")" ::: "memory")
; #define PG8_WAIT_L(n) asm volatile("s_waitcnt lgkmcnt(" #n ")" ::: "memory")
; #define PG8_BAR __builtin_amdgcn_s_barrier()
; #define PG8_SCHED __builtin_amdgcn_sched_barrier(0)
; template <class Epi, class Sched, bool ALIGN_EPI = false, bool SP2 = false>
; __device__ __forceinline__ void gemm_phase(PG8_LAS unsigned char* lds, const Gemm g, const Sched& S, const Epi& E) {
;     ...
;             PG8_WAIT_V(8); PG8_WAIT_L(0); PG8_BAR; PG8_MMA(1, 0, At, B0); PG8_MMA(1, 1, At, B1); PG8_BAR; PG8_SCHED;
;             PG8_LDB(B0, 1, 0); PG8_LDB(B1, 1, 1); PG8_SCHED; PG8_LDA(At, 1, 0); PG8_STAGE(PG8_SA(0, 1), a2 + hstep, voffA);
;             PG8_WAIT_V(8); PG8_WAIT_L(0); PG8_BAR; PG8_MMA(0, 0, At, B0); PG8_MMA(0, 1, At, B1); PG8_BAR; PG8_SCHED;
	v_mfma_f32_16x16x32_bf16 v[62:65], v[110:113], v[162:165], v[62:65]
	v_mfma_f32_16x16x32_bf16 v[62:65], v[118:121], v[166:169], v[62:65]
	v_mfma_f32_16x16x32_bf16 v[46:49], v[110:113], v[170:173], v[46:49]
	v_mfma_f32_16x16x32_bf16 v[46:49], v[118:121], v[174:177], v[46:49]
	v_mfma_f32_16x16x32_bf16 v[30:33], v[110:113], v[178:181], v[30:33]
	v_mfma_f32_16x16x32_bf16 v[30:33], v[118:121], v[182:185], v[30:33]
	v_mfma_f32_16x16x32_bf16 v[14:17], v[110:113], v[186:189], v[14:17]
	v_mfma_f32_16x16x32_bf16 v[14:17], v[118:121], v[190:193], v[14:17]
	v_mfma_f32_16x16x32_bf16 v[58:61], v[138:141], v[162:165], v[58:61]
	v_mfma_f32_16x16x32_bf16 v[58:61], v[142:145], v[166:169], v[58:61]
	v_mfma_f32_16x16x32_bf16 v[42:45], v[138:141], v[170:173], v[42:45]
	v_mfma_f32_16x16x32_bf16 v[42:45], v[142:145], v[174:177], v[42:45]
	v_mfma_f32_16x16x32_bf16 v[26:29], v[138:141], v[178:181], v[26:29]
	v_mfma_f32_16x16x32_bf16 v[26:29], v[142:145], v[182:185], v[26:29]
	v_mfma_f32_16x16x32_bf16 v[10:13], v[138:141], v[186:189], v[10:13]
	v_mfma_f32_16x16x32_bf16 v[10:13], v[142:145], v[190:193], v[10:13]
	v_mfma_f32_16x16x32_bf16 v[54:57], v[146:149], v[162:165], v[54:57]
	v_mfma_f32_16x16x32_bf16 v[54:57], v[150:153], v[166:169], v[54:57]
	v_mfma_f32_16x16x32_bf16 v[38:41], v[146:149], v[170:173], v[38:41]
	v_mfma_f32_16x16x32_bf16 v[38:41], v[150:153], v[174:177], v[38:41]
	v_mfma_f32_16x16x32_bf16 v[22:25], v[146:149], v[178:181], v[22:25]
	v_mfma_f32_16x16x32_bf16 v[22:25], v[150:153], v[182:185], v[22:25]
	v_mfma_f32_16x16x32_bf16 v[6:9], v[146:149], v[186:189], v[6:9]
	v_mfma_f32_16x16x32_bf16 v[6:9], v[150:153], v[190:193], v[6:9]
	v_mfma_f32_16x16x32_bf16 v[50:53], v[154:157], v[162:165], v[50:53]
	v_mfma_f32_16x16x32_bf16 v[50:53], v[158:161], v[166:169], v[50:53]
	v_mfma_f32_16x16x32_bf16 v[34:37], v[154:157], v[170:173], v[34:37]
	v_mfma_f32_16x16x32_bf16 v[34:37], v[158:161], v[174:177], v[34:37]
	v_mfma_f32_16x16x32_bf16 v[18:21], v[154:157], v[178:181], v[18:21]
	v_mfma_f32_16x16x32_bf16 v[18:21], v[158:161], v[182:185], v[18:21]
	v_mfma_f32_16x16x32_bf16 v[2:5], v[154:157], v[186:189], v[2:5]
	v_mfma_f32_16x16x32_bf16 v[2:5], v[158:161], v[190:193], v[2:5]
	s_barrier
	s_add_i32 s18, 0, 0x18000
	s_add_i32 vcc_hi, 0, 0x1c000
	v_add_u32_e32 v142, s18, v245
	v_add_u32_e32 v158, vcc_hi, v245
	ds_read_b128 v[110:113], v142
	ds_read_b128 v[118:121], v142 offset:1024
	ds_read_b128 v[138:141], v142 offset:2048
	ds_read_b128 v[142:145], v142 offset:3072
	ds_read_b128 v[146:149], v158
	ds_read_b128 v[150:153], v158 offset:1024
	ds_read_b128 v[154:157], v158 offset:2048
	ds_read_b128 v[158:161], v158 offset:3072
	s_add_u32 s38, s46, s58
	s_addc_u32 s39, s47, 0
	s_mov_b32 m0, s94
	v_lshl_add_u64 v[222:223], s[38:39], 0, v[194:195]
	ds_read_b128 v[162:165], v247 offset:32768
	ds_read_b128 v[166:169], v247 offset:33792
	ds_read_b128 v[170:173], v247 offset:34816
	ds_read_b128 v[174:177], v247 offset:35840
	ds_read_b128 v[178:181], v247 offset:36864
	ds_read_b128 v[182:185], v247 offset:37888
	ds_read_b128 v[186:189], v247 offset:38912
	ds_read_b128 v[190:193], v247 offset:39936
	global_load_lds_dwordx4 v[222:223], off
	v_lshl_add_u64 v[222:223], s[38:39], 0, v[202:203]
	s_mov_b32 m0, s95
	s_nop 0
	global_load_lds_dwordx4 v[222:223], off
	s_waitcnt vmcnt(8)
	s_waitcnt lgkmcnt(0)
	s_barrier
	v_mfma_f32_16x16x32_bf16 v[130:133], v[110:113], v[162:165], v[130:133]
	v_mfma_f32_16x16x32_bf16 v[130:133], v[118:121], v[166:169], v[130:133]
	v_mfma_f32_16x16x32_bf16 v[114:117], v[110:113], v[170:173], v[114:117]
	v_mfma_f32_16x16x32_bf16 v[114:117], v[118:121], v[174:177], v[114:117]
	v_mfma_f32_16x16x32_bf16 v[94:97], v[110:113], v[178:181], v[94:97]
	v_mfma_f32_16x16x32_bf16 v[94:97], v[118:121], v[182:185], v[94:97]
	v_mfma_f32_16x16x32_bf16 v[78:81], v[110:113], v[186:189], v[78:81]
	v_mfma_f32_16x16x32_bf16 v[78:81], v[118:121], v[190:193], v[78:81]
	v_mfma_f32_16x16x32_bf16 v[134:137], v[138:141], v[162:165], v[134:137]
	v_mfma_f32_16x16x32_bf16 v[134:137], v[142:145], v[166:169], v[134:137]
	v_mfma_f32_16x16x32_bf16 v[106:109], v[138:141], v[170:173], v[106:109]
	v_mfma_f32_16x16x32_bf16 v[106:109], v[142:145], v[174:177], v[106:109]
	v_mfma_f32_16x16x32_bf16 v[90:93], v[138:141], v[178:181], v[90:93]
	v_mfma_f32_16x16x32_bf16 v[90:93], v[142:145], v[182:185], v[90:93]
	v_mfma_f32_16x16x32_bf16 v[74:77], v[138:141], v[186:189], v[74:77]
	v_mfma_f32_16x16x32_bf16 v[74:77], v[142:145], v[190:193], v[74:77]
	v_mfma_f32_16x16x32_bf16 v[126:129], v[146:149], v[162:165], v[126:129]
	v_mfma_f32_16x16x32_bf16 v[126:129], v[150:153], v[166:169], v[126:129]
	v_mfma_f32_16x16x32_bf16 v[102:105], v[146:149], v[170:173], v[102:105]
	v_mfma_f32_16x16x32_bf16 v[102:105], v[150:153], v[174:177], v[102:105]
	v_mfma_f32_16x16x32_bf16 v[86:89], v[146:149], v[178:181], v[86:89]
	v_mfma_f32_16x16x32_bf16 v[86:89], v[150:153], v[182:185], v[86:89]
	v_mfma_f32_16x16x32_bf16 v[70:73], v[146:149], v[186:189], v[70:73]
	v_mfma_f32_16x16x32_bf16 v[70:73], v[150:153], v[190:193], v[70:73]
	v_mfma_f32_16x16x32_bf16 v[122:125], v[154:157], v[162:165], v[122:125]
	v_mfma_f32_16x16x32_bf16 v[122:125], v[158:161], v[166:169], v[122:125]
	v_mfma_f32_16x16x32_bf16 v[98:101], v[154:157], v[170:173], v[98:101]
	v_mfma_f32_16x16x32_bf16 v[98:101], v[158:161], v[174:177], v[98:101]
	v_mfma_f32_16x16x32_bf16 v[82:85], v[154:157], v[178:181], v[82:85]
	v_mfma_f32_16x16x32_bf16 v[82:85], v[158:161], v[182:185], v[82:85]
	v_mfma_f32_16x16x32_bf16 v[66:69], v[154:157], v[186:189], v[66:69]
	v_mfma_f32_16x16x32_bf16 v[66:69], v[158:161], v[190:193], v[66:69]
	s_barrier
; #define PG8_STAGE(bufoff, gbase, voff) do { _Pragma("unroll") for (int _i = 0; _i < 2; ++_i) \
;         __builtin_amdgcn_global_load_lds((const unsigned*)((const char*)(gbase) + (voff)[_i]), (PG8_LAS unsigned*)(lds + (bufoff) + ldsw + _i * 8192), 16, 0, 0); } while (0)
; #define PG8_LDA(dst, b, h) do { _Pragma("unroll") for (int m = 0; m < 4; ++m) _Pragma("unroll") for (int k = 0; k < 2; ++k) dst[m][k] = *(const PG8_LAS bf16x8*)(lds + PG8_SA(b, h) + aoff + m * 2048 + k * 1024); } while (0)
; #define PG8_MMA(ai, bj, At, Bt) do { __builtin_amdgcn_s_setprio(1); _Pragma("unroll") for (int m = 0; m < 4; ++m) _Pragma("unroll") for (int n = 0; n < 2; ++n) _Pragma("unroll") for (int k = 0; k < 2; ++k) \
;         acc[ai][bj][m][n] = __builtin_amdgcn_mfma_f32_16x16x32_bf16(Bt[n][k], At[m][k], acc[ai][bj][m][n], 0, 0, 0); __builtin_amdgcn_s_setprio(0); } while (0)
; #define PG8_WAIT_V(n) asm volatile("s_waitcnt vmcnt(" #n ")" ::: "memory")
; #define PG8_WAIT_L(n) asm volatile("s_waitcnt lgkmcnt(" #n ")" ::: "memory")
; #define PG8_BAR __builtin_amdgcn_s_barrier()
; #define PG8_SCHED __builtin_amdgcn_sched_barrier(0)
; template <class Epi, class Sched, bool ALIGN_EPI = false, bool SP2 = false>
; __device__ __forceinline__ void gemm_phase(PG8_LAS unsigned char* lds, const Gemm g, const Sched& S, const Epi& E) {
;     ...
;             PG8_LDA(At, 1, 1); PG8_STAGE(PG8_SB(1, 0), b3, voffB); PG8_STAGE(PG8_SB(1, 1), b3 + hstep, voffB); PG8_STAGE(PG8_SA(1, 0), a3, voffA);
;             PG8_WAIT_V(8); PG8_WAIT_L(0); PG8_BAR; PG8_MMA(1, 0, At, B0); PG8_MMA(1, 1, At, B1); PG8_BAR; PG8_SCHED;
;     ...
;         if constexpr (ALIGN_EPI) { if (wr == 0) PG8_BAR; }
	s_add_i32 s18, s18, s6
	v_lshl_add_u64 v[210:211], v[210:211], 0, s[30:31]
	s_mov_b32 m0, s18
	ds_read_b128 v[162:165], v247 offset:49152
	ds_read_b128 v[166:169], v247 offset:50176
	ds_read_b128 v[170:173], v247 offset:51200
	ds_read_b128 v[174:177], v247 offset:52224
	ds_read_b128 v[178:181], v247 offset:53248
	ds_read_b128 v[182:185], v247 offset:54272
	ds_read_b128 v[186:189], v247 offset:55296
	ds_read_b128 v[190:193], v247 offset:56320
	global_load_lds_dwordx4 v[210:211], off
	v_lshl_add_u64 v[210:211], v[212:213], 0, s[30:31]
	s_add_i32 m0, s18, 0x2000
	s_add_i32 s18, vcc_hi, s6
	global_load_lds_dwordx4 v[210:211], off
	v_lshl_add_u64 v[210:211], v[214:215], 0, s[30:31]
	s_mov_b32 m0, s18
	s_nop 0
	global_load_lds_dwordx4 v[210:211], off
	v_lshl_add_u64 v[210:211], v[216:217], 0, s[30:31]
	s_add_i32 m0, s18, 0x2000
	s_nop 0
	global_load_lds_dwordx4 v[210:211], off
	v_lshl_add_u64 v[210:211], v[218:219], 0, s[30:31]
	s_mov_b32 m0, s97
	s_nop 0
	global_load_lds_dwordx4 v[210:211], off
	v_lshl_add_u64 v[210:211], v[220:221], 0, s[30:31]
	s_mov_b32 m0, s98
	s_nop 0
	global_load_lds_dwordx4 v[210:211], off
	s_waitcnt vmcnt(8)
	s_waitcnt lgkmcnt(0)
	s_barrier
	v_mfma_f32_16x16x32_bf16 v[62:65], v[110:113], v[162:165], v[62:65]
	v_mfma_f32_16x16x32_bf16 v[62:65], v[118:121], v[166:169], v[62:65]
	v_mfma_f32_16x16x32_bf16 v[46:49], v[110:113], v[170:173], v[46:49]
	v_mfma_f32_16x16x32_bf16 v[46:49], v[118:121], v[174:177], v[46:49]
	v_mfma_f32_16x16x32_bf16 v[30:33], v[110:113], v[178:181], v[30:33]
	v_mfma_f32_16x16x32_bf16 v[30:33], v[118:121], v[182:185], v[30:33]
	v_mfma_f32_16x16x32_bf16 v[14:17], v[110:113], v[186:189], v[14:17]
	v_mfma_f32_16x16x32_bf16 v[14:17], v[118:121], v[190:193], v[14:17]
	v_mfma_f32_16x16x32_bf16 v[58:61], v[138:141], v[162:165], v[58:61]
	v_mfma_f32_16x16x32_bf16 v[58:61], v[142:145], v[166:169], v[58:61]
	v_mfma_f32_16x16x32_bf16 v[42:45], v[138:141], v[170:173], v[42:45]
	v_mfma_f32_16x16x32_bf16 v[42:45], v[142:145], v[174:177], v[42:45]
	v_mfma_f32_16x16x32_bf16 v[26:29], v[138:141], v[178:181], v[26:29]
	v_mfma_f32_16x16x32_bf16 v[26:29], v[142:145], v[182:185], v[26:29]
	v_mfma_f32_16x16x32_bf16 v[10:13], v[138:141], v[186:189], v[10:13]
	v_mfma_f32_16x16x32_bf16 v[10:13], v[142:145], v[190:193], v[10:13]
	v_mfma_f32_16x16x32_bf16 v[54:57], v[146:149], v[162:165], v[54:57]
	v_mfma_f32_16x16x32_bf16 v[54:57], v[150:153], v[166:169], v[54:57]
	v_mfma_f32_16x16x32_bf16 v[38:41], v[146:149], v[170:173], v[38:41]
	v_mfma_f32_16x16x32_bf16 v[38:41], v[150:153], v[174:177], v[38:41]
	v_mfma_f32_16x16x32_bf16 v[22:25], v[146:149], v[178:181], v[22:25]
	v_mfma_f32_16x16x32_bf16 v[22:25], v[150:153], v[182:185], v[22:25]
	v_mfma_f32_16x16x32_bf16 v[6:9], v[146:149], v[186:189], v[6:9]
	v_mfma_f32_16x16x32_bf16 v[6:9], v[150:153], v[190:193], v[6:9]
	v_mfma_f32_16x16x32_bf16 v[50:53], v[154:157], v[162:165], v[50:53]
	v_mfma_f32_16x16x32_bf16 v[50:53], v[158:161], v[166:169], v[50:53]
	v_mfma_f32_16x16x32_bf16 v[34:37], v[154:157], v[170:173], v[34:37]
	v_mfma_f32_16x16x32_bf16 v[34:37], v[158:161], v[174:177], v[34:37]
	v_mfma_f32_16x16x32_bf16 v[18:21], v[154:157], v[178:181], v[18:21]
	v_mfma_f32_16x16x32_bf16 v[18:21], v[158:161], v[182:185], v[18:21]
	v_mfma_f32_16x16x32_bf16 v[2:5], v[154:157], v[186:189], v[2:5]
	v_mfma_f32_16x16x32_bf16 v[2:5], v[158:161], v[190:193], v[2:5]
	s_barrier
	s_add_u32 s48, s48, 0x100
	s_addc_u32 s49, s49, 0
	s_add_u32 s50, s50, 0x100
	s_addc_u32 s51, s51, 0
	s_cmp_ge_u32 vcc_lo, s96
	s_mov_b32 s46, vcc_lo
	s_cbranch_scc0 .LBB0_274
	s_and_b64 vcc, exec, s[72:73]
	s_cbranch_vccz .LBB0_277
	s_barrier

; #define PG8_STAGE(bufoff, gbase, voff) do { _Pragma("unroll") for (int _i = 0; _i < 2; ++_i) \
;         __builtin_amdgcn_global_load_lds((const unsigned*)((const char*)(gbase) + (voff)[_i]), (PG8_LAS unsigned*)(lds + (bufoff) + ldsw + _i * 8192), 16, 0, 0); } while (0)
; #define PG8_LDA(dst, b, h) do { _Pragma("unroll") for (int m = 0; m < 4; ++m) _Pragma("unroll") for (int k = 0; k < 2; ++k) dst[m][k] = *(const PG8_LAS bf16x8*)(lds + PG8_SA(b, h) + aoff + m * 2048 + k * 1024); } while (0)
; #define PG8_LDB(dst, b, h) do { _Pragma("unroll") for (int n = 0; n < 2; ++n) _Pragma("unroll") for (int k = 0; k < 2; ++k) dst[n][k] = *(const PG8_LAS bf16x8*)(lds + PG8_SB(b, h) + boff + n * 2048 + k * 1024); } while (0)
; #define PG8_MMA(ai, bj, At, Bt) do { __builtin_amdgcn_s_setprio(1); _Pragma("unroll") for (int m = 0; m < 4; ++m) _Pragma("unroll") for (int n = 0; n < 2; ++n) _Pragma("unroll") for (int k = 0; k < 2; ++k) \
;         acc[ai][bj][m][n] = __builtin_amdgcn_mfma_f32_16x16x32_bf16(Bt[n][k], At[m][k], acc[ai][bj][m][n], 0, 0, 0); __builtin_amdgcn_s_setprio(0); } while (0)
; #define PG8_WAIT_V(n) asm volatile("s_waitcnt vmcnt(" #n ")" ::: "memory")
; #define PG8_WAIT_L(n) asm volatile("s_waitcnt lgkmcnt(" #n ")" ::: "memory")
; #define PG8_BAR __builtin_amdgcn_s_barrier()
; template <class Epi, class Sched, bool ALIGN_EPI = false, bool SP2 = false>
; __device__ __forceinline__ void gemm_phase(PG8_LAS unsigned char* lds, const Gemm g, const Sched& S, const Epi& E) {
;     ...
;             const char* a1 = cA + (size_t)(t + 1) * kstep;
;             const char* a2 = last ? nA : cA + (size_t)(t + 2) * kstep; const char* b2 = last ? nB : cB + (size_t)(t + 2) * kstep;
;             const char* a3 = a2 + kstep; const char* b3 = b2 + kstep;
;             if (last && has_next) S.a_ready(nxt);
;             if constexpr (SP2) {
;             PG8_LDB(B0, 0, 0); PG8_LDB(B1, 0, 1); PG8_SCHED; PG8_LDA(At, 0, 0); PG8_STAGE(PG8_SA(1, 1), a1 + hstep, voffA);
;             PG8_WAIT_V(8); PG8_WAIT_L(0); PG8_BAR; PG8_MMA(0, 0, At, B0); PG8_MMA(0, 1, At, B1); PG8_BAR; PG8_SCHED;
;             PG8_LDA(At, 0, 1); PG8_STAGE(PG8_SB(0, 0), b2, voffB); PG8_STAGE(PG8_SB(0, 1), b2 + hstep, voffB); PG8_STAGE(PG8_SA(0, 0), a2, voffA);
;             PG8_WAIT_V(8); PG8_WAIT_L(0); PG8_BAR; PG8_MMA(1, 0, At, B0); PG8_MMA(1, 1, At, B1); PG8_BAR; PG8_SCHED;
.LBB0_408:
	s_add_u32 s38, s48, 0xfffc0080
	s_addc_u32 s39, s49, -1
	s_add_i32 s85, 0, 0x10000
	s_cmp_eq_u32 s84, 12
	s_cselect_b32 s73, s21, s39
	s_cselect_b32 s72, s27, s38
	v_add_u32_e32 v0, s85, v167
	s_cselect_b32 s47, s29, s69
	s_cselect_b32 s46, s33, s53
	s_add_i32 s38, 0, 0x14000
	ds_read_b128 v[142:145], v0
	ds_read_b128 v[146:149], v0 offset:1024
	ds_read_b128 v[150:153], v0 offset:2048
	ds_read_b128 v[154:157], v0 offset:3072
	v_add_u32_e32 v0, s38, v167
	ds_read_b128 v[158:161], v0
	ds_read_b128 v[162:165], v0 offset:1024
	ds_read_b128 v[172:175], v0 offset:2048
	ds_read_b128 v[176:179], v0 offset:3072
	v_lshl_add_u64 v[218:219], s[48:49], 0, v[138:139]
	s_add_i32 m0, s76, 0xc000
	ds_read_b128 v[180:183], v170
	ds_read_b128 v[184:187], v170 offset:1024
	ds_read_b128 v[188:191], v170 offset:2048
	ds_read_b128 v[192:195], v170 offset:3072
	ds_read_b128 v[202:205], v170 offset:4096
	ds_read_b128 v[206:209], v170 offset:5120
	ds_read_b128 v[210:213], v170 offset:6144
	ds_read_b128 v[214:217], v170 offset:7168
	global_load_lds_dwordx4 v[218:219], off
	v_lshl_add_u64 v[218:219], s[48:49], 0, v[140:141]
	s_add_i32 m0, s76, 0xe000
	s_nop 0
	global_load_lds_dwordx4 v[218:219], off
	s_waitcnt vmcnt(8)
	s_waitcnt lgkmcnt(0)
	s_barrier
	v_mfma_f32_16x16x32_bf16 v[122:125], v[142:145], v[180:183], v[122:125]
	v_mfma_f32_16x16x32_bf16 v[122:125], v[146:149], v[184:187], v[122:125]
	v_mfma_f32_16x16x32_bf16 v[106:109], v[142:145], v[188:191], v[106:109]
	v_mfma_f32_16x16x32_bf16 v[106:109], v[146:149], v[192:195], v[106:109]
	v_mfma_f32_16x16x32_bf16 v[90:93], v[142:145], v[202:205], v[90:93]
	v_mfma_f32_16x16x32_bf16 v[90:93], v[146:149], v[206:209], v[90:93]
	v_mfma_f32_16x16x32_bf16 v[74:77], v[142:145], v[210:213], v[74:77]
	v_mfma_f32_16x16x32_bf16 v[74:77], v[146:149], v[214:217], v[74:77]
	v_mfma_f32_16x16x32_bf16 v[126:129], v[150:153], v[180:183], v[126:129]
	v_mfma_f32_16x16x32_bf16 v[126:129], v[154:157], v[184:187], v[126:129]
	v_mfma_f32_16x16x32_bf16 v[110:113], v[150:153], v[188:191], v[110:113]
	v_mfma_f32_16x16x32_bf16 v[110:113], v[154:157], v[192:195], v[110:113]
	v_mfma_f32_16x16x32_bf16 v[94:97], v[150:153], v[202:205], v[94:97]
	v_mfma_f32_16x16x32_bf16 v[94:97], v[154:157], v[206:209], v[94:97]
	v_mfma_f32_16x16x32_bf16 v[78:81], v[150:153], v[210:213], v[78:81]
	v_mfma_f32_16x16x32_bf16 v[78:81], v[154:157], v[214:217], v[78:81]
	v_mfma_f32_16x16x32_bf16 v[114:117], v[158:161], v[180:183], v[114:117]
	v_mfma_f32_16x16x32_bf16 v[114:117], v[162:165], v[184:187], v[114:117]
	v_mfma_f32_16x16x32_bf16 v[98:101], v[158:161], v[188:191], v[98:101]
	v_mfma_f32_16x16x32_bf16 v[98:101], v[162:165], v[192:195], v[98:101]
	v_mfma_f32_16x16x32_bf16 v[82:85], v[158:161], v[202:205], v[82:85]
	v_mfma_f32_16x16x32_bf16 v[82:85], v[162:165], v[206:209], v[82:85]
	v_mfma_f32_16x16x32_bf16 v[66:69], v[158:161], v[210:213], v[66:69]
	v_mfma_f32_16x16x32_bf16 v[66:69], v[162:165], v[214:217], v[66:69]
	v_mfma_f32_16x16x32_bf16 v[118:121], v[172:175], v[180:183], v[118:121]
	v_mfma_f32_16x16x32_bf16 v[118:121], v[176:179], v[184:187], v[118:121]
	v_mfma_f32_16x16x32_bf16 v[102:105], v[172:175], v[188:191], v[102:105]
	v_mfma_f32_16x16x32_bf16 v[102:105], v[176:179], v[192:195], v[102:105]
	v_mfma_f32_16x16x32_bf16 v[86:89], v[172:175], v[202:205], v[86:89]
	v_mfma_f32_16x16x32_bf16 v[86:89], v[176:179], v[206:209], v[86:89]
	v_mfma_f32_16x16x32_bf16 v[70:73], v[172:175], v[210:213], v[70:73]
	v_mfma_f32_16x16x32_bf16 v[70:73], v[176:179], v[214:217], v[70:73]
	s_barrier
	s_add_i32 s39, s85, s75
	v_lshl_add_u64 v[218:219], s[46:47], 0, v[134:135]
	s_mov_b32 m0, s39
	ds_read_b128 v[180:183], v170 offset:16384
	ds_read_b128 v[184:187], v170 offset:17408
	ds_read_b128 v[188:191], v170 offset:18432
	ds_read_b128 v[192:195], v170 offset:19456
	ds_read_b128 v[202:205], v170 offset:20480
	ds_read_b128 v[206:209], v170 offset:21504
	ds_read_b128 v[210:213], v170 offset:22528
	ds_read_b128 v[214:217], v170 offset:23552
	global_load_lds_dwordx4 v[218:219], off
	s_add_i32 m0, s39, 0x2000
	s_add_u32 s92, s46, 0x40000
	v_lshl_add_u64 v[220:221], s[46:47], 0, v[130:131]
	s_addc_u32 s93, s47, 0
	s_add_i32 s38, s38, s75
	global_load_lds_dwordx4 v[220:221], off
	v_lshl_add_u64 v[222:223], s[92:93], 0, v[134:135]
	s_mov_b32 m0, s38
	v_lshl_add_u64 v[224:225], s[72:73], 0, v[132:133]
	global_load_lds_dwordx4 v[222:223], off
	v_lshl_add_u64 v[222:223], s[92:93], 0, v[130:131]
	s_add_i32 m0, s38, 0x2000
	s_nop 0
	global_load_lds_dwordx4 v[222:223], off
	v_lshl_add_u64 v[222:223], s[72:73], 0, v[136:137]
	s_mov_b32 m0, s76
	s_nop 0
	global_load_lds_dwordx4 v[222:223], off
	s_mov_b32 m0, s77
	s_nop 0
	global_load_lds_dwordx4 v[224:225], off
	s_waitcnt vmcnt(8)
	s_waitcnt lgkmcnt(0)
	s_barrier
; #define PG8_STAGE(bufoff, gbase, voff) do { _Pragma("unroll") for (int _i = 0; _i < 2; ++_i) \
;         __builtin_amdgcn_global_load_lds((const unsigned*)((const char*)(gbase) + (voff)[_i]), (PG8_LAS unsigned*)(lds + (bufoff) + ldsw + _i * 8192), 16, 0, 0); } while (0)
; #define PG8_LDA(dst, b, h) do { _Pragma("unroll") for (int m = 0; m < 4; ++m) _Pragma("unroll") for (int k = 0; k < 2; ++k) dst[m][k] = *(const PG8_LAS bf16x8*)(lds + PG8_SA(b, h) + aoff + m * 2048 + k * 1024); } while (0)
; #define PG8_LDB(dst, b, h) do { _Pragma("unroll") for (int n = 0; n < 2; ++n) _Pragma("unroll") for (int k = 0; k < 2; ++k) dst[n][k] = *(const PG8_LAS bf16x8*)(lds + PG8_SB(b, h) + boff + n * 2048 + k * 1024); } while (0)
; #define PG8_MMA(ai, bj, At, Bt) do { __builtin_amdgcn_s_setprio(1); _Pragma("unroll") for (int m = 0; m < 4; ++m) _Pragma("unroll") for (int n = 0; n < 2; ++n) _Pragma("unroll") for (int k = 0; k < 2; ++k) \
;         acc[ai][bj][m][n] = __builtin_amdgcn_mfma_f32_16x16x32_bf16(Bt[n][k], At[m][k], acc[ai][bj][m][n], 0, 0, 0); __builtin_amdgcn_s_setprio(0); } while (0)
; #define PG8_WAIT_V(n) asm volatile("s_waitcnt vmcnt(" #n ")" ::: "memory")
; #define PG8_WAIT_L(n) asm volatile("s_waitcnt lgkmcnt(" #n ")" ::: "memory")
; #define PG8_BAR __builtin_amdgcn_s_barrier()
; #define PG8_SCHED __builtin_amdgcn_sched_barrier(0)
; template <class Epi, class Sched, bool ALIGN_EPI = false, bool SP2 = false>
; __device__ __forceinline__ void gemm_phase(PG8_LAS unsigned char* lds, const Gemm g, const Sched& S, const Epi& E) {
;     ...
;             PG8_WAIT_V(8); PG8_WAIT_L(0); PG8_BAR; PG8_MMA(1, 0, At, B0); PG8_MMA(1, 1, At, B1); PG8_BAR; PG8_SCHED;
;             PG8_LDB(B0, 1, 0); PG8_LDB(B1, 1, 1); PG8_SCHED; PG8_LDA(At, 1, 0); PG8_STAGE(PG8_SA(0, 1), a2 + hstep, voffA);
;             PG8_WAIT_V(8); PG8_WAIT_L(0); PG8_BAR; PG8_MMA(0, 0, At, B0); PG8_MMA(0, 1, At, B1); PG8_BAR; PG8_SCHED;
	v_mfma_f32_16x16x32_bf16 v[58:61], v[142:145], v[180:183], v[58:61]
	v_mfma_f32_16x16x32_bf16 v[58:61], v[146:149], v[184:187], v[58:61]
	v_mfma_f32_16x16x32_bf16 v[42:45], v[142:145], v[188:191], v[42:45]
	v_mfma_f32_16x16x32_bf16 v[42:45], v[146:149], v[192:195], v[42:45]
	v_mfma_f32_16x16x32_bf16 v[26:29], v[142:145], v[202:205], v[26:29]
	v_mfma_f32_16x16x32_bf16 v[26:29], v[146:149], v[206:209], v[26:29]
	v_mfma_f32_16x16x32_bf16 v[10:13], v[142:145], v[210:213], v[10:13]
	v_mfma_f32_16x16x32_bf16 v[10:13], v[146:149], v[214:217], v[10:13]
	v_mfma_f32_16x16x32_bf16 v[62:65], v[150:153], v[180:183], v[62:65]
	v_mfma_f32_16x16x32_bf16 v[62:65], v[154:157], v[184:187], v[62:65]
	v_mfma_f32_16x16x32_bf16 v[46:49], v[150:153], v[188:191], v[46:49]
	v_mfma_f32_16x16x32_bf16 v[46:49], v[154:157], v[192:195], v[46:49]
	v_mfma_f32_16x16x32_bf16 v[30:33], v[150:153], v[202:205], v[30:33]
	v_mfma_f32_16x16x32_bf16 v[30:33], v[154:157], v[206:209], v[30:33]
	v_mfma_f32_16x16x32_bf16 v[14:17], v[150:153], v[210:213], v[14:17]
	v_mfma_f32_16x16x32_bf16 v[14:17], v[154:157], v[214:217], v[14:17]
	v_mfma_f32_16x16x32_bf16 v[50:53], v[158:161], v[180:183], v[50:53]
	v_mfma_f32_16x16x32_bf16 v[50:53], v[162:165], v[184:187], v[50:53]
	v_mfma_f32_16x16x32_bf16 v[34:37], v[158:161], v[188:191], v[34:37]
	v_mfma_f32_16x16x32_bf16 v[34:37], v[162:165], v[192:195], v[34:37]
	v_mfma_f32_16x16x32_bf16 v[18:21], v[158:161], v[202:205], v[18:21]
	v_mfma_f32_16x16x32_bf16 v[18:21], v[162:165], v[206:209], v[18:21]
	v_mfma_f32_16x16x32_bf16 v[2:5], v[158:161], v[210:213], v[2:5]
	v_mfma_f32_16x16x32_bf16 v[2:5], v[162:165], v[214:217], v[2:5]
	v_mfma_f32_16x16x32_bf16 v[54:57], v[172:175], v[180:183], v[54:57]
	v_mfma_f32_16x16x32_bf16 v[54:57], v[176:179], v[184:187], v[54:57]
	v_mfma_f32_16x16x32_bf16 v[38:41], v[172:175], v[188:191], v[38:41]
	v_mfma_f32_16x16x32_bf16 v[38:41], v[176:179], v[192:195], v[38:41]
	v_mfma_f32_16x16x32_bf16 v[22:25], v[172:175], v[202:205], v[22:25]
	v_mfma_f32_16x16x32_bf16 v[22:25], v[176:179], v[206:209], v[22:25]
	v_mfma_f32_16x16x32_bf16 v[6:9], v[172:175], v[210:213], v[6:9]
	v_mfma_f32_16x16x32_bf16 v[6:9], v[176:179], v[214:217], v[6:9]
	s_barrier
	s_add_i32 s38, 0, 0x18000
	v_add_u32_e32 v0, s38, v167
	s_add_i32 s39, 0, 0x1c000
	ds_read_b128 v[142:145], v0
	ds_read_b128 v[146:149], v0 offset:1024
	ds_read_b128 v[150:153], v0 offset:2048
	ds_read_b128 v[154:157], v0 offset:3072
	v_add_u32_e32 v0, s39, v167
	ds_read_b128 v[158:161], v0
	ds_read_b128 v[162:165], v0 offset:1024
	ds_read_b128 v[172:175], v0 offset:2048
	ds_read_b128 v[176:179], v0 offset:3072
	s_add_u32 s72, s72, 0x40000
	s_addc_u32 s73, s73, 0
	s_mov_b32 m0, s78
	v_lshl_add_u64 v[226:227], s[72:73], 0, v[136:137]
	ds_read_b128 v[180:183], v170 offset:32768
	ds_read_b128 v[184:187], v170 offset:33792
	ds_read_b128 v[188:191], v170 offset:34816
	ds_read_b128 v[192:195], v170 offset:35840
	ds_read_b128 v[202:205], v170 offset:36864
	ds_read_b128 v[206:209], v170 offset:37888
	ds_read_b128 v[210:213], v170 offset:38912
	ds_read_b128 v[214:217], v170 offset:39936
	global_load_lds_dwordx4 v[226:227], off
	v_lshl_add_u64 v[226:227], s[72:73], 0, v[132:133]
	s_mov_b32 m0, s79
	s_nop 0
	global_load_lds_dwordx4 v[226:227], off
	s_waitcnt vmcnt(8)
	s_waitcnt lgkmcnt(0)
	s_barrier
	v_mfma_f32_16x16x32_bf16 v[122:125], v[142:145], v[180:183], v[122:125]
	v_mfma_f32_16x16x32_bf16 v[122:125], v[146:149], v[184:187], v[122:125]
	v_mfma_f32_16x16x32_bf16 v[106:109], v[142:145], v[188:191], v[106:109]
	v_mfma_f32_16x16x32_bf16 v[106:109], v[146:149], v[192:195], v[106:109]
	v_mfma_f32_16x16x32_bf16 v[90:93], v[142:145], v[202:205], v[90:93]
	v_mfma_f32_16x16x32_bf16 v[90:93], v[146:149], v[206:209], v[90:93]
	v_mfma_f32_16x16x32_bf16 v[74:77], v[142:145], v[210:213], v[74:77]
	v_mfma_f32_16x16x32_bf16 v[74:77], v[146:149], v[214:217], v[74:77]
	v_mfma_f32_16x16x32_bf16 v[126:129], v[150:153], v[180:183], v[126:129]
	v_mfma_f32_16x16x32_bf16 v[126:129], v[154:157], v[184:187], v[126:129]
	v_mfma_f32_16x16x32_bf16 v[110:113], v[150:153], v[188:191], v[110:113]
	v_mfma_f32_16x16x32_bf16 v[110:113], v[154:157], v[192:195], v[110:113]
	v_mfma_f32_16x16x32_bf16 v[94:97], v[150:153], v[202:205], v[94:97]
	v_mfma_f32_16x16x32_bf16 v[94:97], v[154:157], v[206:209], v[94:97]
	v_mfma_f32_16x16x32_bf16 v[78:81], v[150:153], v[210:213], v[78:81]
	v_mfma_f32_16x16x32_bf16 v[78:81], v[154:157], v[214:217], v[78:81]
	v_mfma_f32_16x16x32_bf16 v[114:117], v[158:161], v[180:183], v[114:117]
	v_mfma_f32_16x16x32_bf16 v[114:117], v[162:165], v[184:187], v[114:117]
	v_mfma_f32_16x16x32_bf16 v[98:101], v[158:161], v[188:191], v[98:101]
	v_mfma_f32_16x16x32_bf16 v[98:101], v[162:165], v[192:195], v[98:101]
	v_mfma_f32_16x16x32_bf16 v[82:85], v[158:161], v[202:205], v[82:85]
	v_mfma_f32_16x16x32_bf16 v[82:85], v[162:165], v[206:209], v[82:85]
	v_mfma_f32_16x16x32_bf16 v[66:69], v[158:161], v[210:213], v[66:69]
	v_mfma_f32_16x16x32_bf16 v[66:69], v[162:165], v[214:217], v[66:69]
	v_mfma_f32_16x16x32_bf16 v[118:121], v[172:175], v[180:183], v[118:121]
	v_mfma_f32_16x16x32_bf16 v[118:121], v[176:179], v[184:187], v[118:121]
	v_mfma_f32_16x16x32_bf16 v[102:105], v[172:175], v[188:191], v[102:105]
	v_mfma_f32_16x16x32_bf16 v[102:105], v[176:179], v[192:195], v[102:105]
	v_mfma_f32_16x16x32_bf16 v[86:89], v[172:175], v[202:205], v[86:89]
	v_mfma_f32_16x16x32_bf16 v[86:89], v[176:179], v[206:209], v[86:89]
	v_mfma_f32_16x16x32_bf16 v[70:73], v[172:175], v[210:213], v[70:73]
	v_mfma_f32_16x16x32_bf16 v[70:73], v[176:179], v[214:217], v[70:73]
	s_barrier
; #define PG8_STAGE(bufoff, gbase, voff) do { _Pragma("unroll") for (int _i = 0; _i < 2; ++_i) \
;         __builtin_amdgcn_global_load_lds((const unsigned*)((const char*)(gbase) + (voff)[_i]), (PG8_LAS unsigned*)(lds + (bufoff) + ldsw + _i * 8192), 16, 0, 0); } while (0)
; #define PG8_LDA(dst, b, h) do { _Pragma("unroll") for (int m = 0; m < 4; ++m) _Pragma("unroll") for (int k = 0; k < 2; ++k) dst[m][k] = *(const PG8_LAS bf16x8*)(lds + PG8_SA(b, h) + aoff + m * 2048 + k * 1024); } while (0)
; #define PG8_WAIT_V(n) asm volatile("s_waitcnt vmcnt(" #n ")" ::: "memory")
; template <class Epi, class Sched, bool ALIGN_EPI = false, bool SP2 = false>
; __device__ __forceinline__ void gemm_phase(PG8_LAS unsigned char* lds, const Gemm g, const Sched& S, const Epi& E) {
;     ...
;             PG8_LDA(At, 1, 1); PG8_STAGE(PG8_SB(1, 0), b3, voffB); PG8_STAGE(PG8_SB(1, 1), b3 + hstep, voffB); PG8_STAGE(PG8_SA(1, 0), a3, voffA);
;             PG8_WAIT_V(8); PG8_WAIT_L(0); PG8_BAR; PG8_MMA(1, 0, At, B0); PG8_MMA(1, 1, At, B1); PG8_BAR; PG8_SCHED;
;             } else {
;             PG8_LDB(B0, 0, 0); PG8_SCHED; PG8_LDA(At, 0, 0); PG8_STAGE(PG8_SA(1, 1), a1 + hstep, voffA);
;             PG8_WAIT_L(8); PG8_BAR; PG8_WAIT_L(0); PG8_MMA(0, 0, At, B0); PG8_BAR; PG8_SCHED;
;             PG8_LDB(B1, 0, 1); PG8_STAGE(PG8_SB(0, 0), b2, voffB);
;             PG8_BAR; PG8_WAIT_L(0); PG8_MMA(0, 1, At, B1); PG8_BAR;
;             PG8_LDA(At, 0, 1); PG8_STAGE(PG8_SA(0, 0), a2, voffA);
;             PG8_BAR; PG8_WAIT_L(0); PG8_MMA(1, 0, At, B0); PG8_BAR; PG8_SCHED;
;             PG8_STAGE(PG8_SB(0, 1), b2 + hstep, voffB);
;             PG8_WAIT_V(6); PG8_BAR; PG8_MMA(1, 1, At, B1); PG8_BAR;
;             PG8_LDB(B0, 1, 0); PG8_SCHED; PG8_LDA(At, 1, 0); PG8_STAGE(PG8_SA(0, 1), a2 + hstep, voffA);
;             PG8_WAIT_L(8); PG8_BAR; PG8_WAIT_L(0); PG8_MMA(0, 0, At, B0); PG8_BAR; PG8_SCHED;
;             PG8_LDB(B1, 1, 1); PG8_STAGE(PG8_SB(1, 0), b3, voffB);
;             PG8_BAR; PG8_WAIT_L(0); PG8_MMA(0, 1, At, B1); PG8_BAR;
;             PG8_LDA(At, 1, 1); PG8_STAGE(PG8_SA(1, 0), a3, voffA);
;             PG8_BAR; PG8_WAIT_L(0); PG8_MMA(1, 0, At, B0); PG8_BAR; PG8_SCHED;
;             PG8_STAGE(PG8_SB(1, 1), b3 + hstep, voffB);
;             PG8_WAIT_V(6); PG8_BAR; PG8_MMA(1, 1, At, B1); PG8_BAR;
;             }
;         }
;         if constexpr (ALIGN_EPI) { if (wr == 0) PG8_BAR; }
	s_add_i32 s38, s38, s75
	v_lshl_add_u64 v[218:219], v[218:219], 0, s[30:31]
	s_mov_b32 m0, s38
	ds_read_b128 v[180:183], v170 offset:49152
	ds_read_b128 v[184:187], v170 offset:50176
	ds_read_b128 v[188:191], v170 offset:51200
	ds_read_b128 v[192:195], v170 offset:52224
	ds_read_b128 v[202:205], v170 offset:53248
	ds_read_b128 v[206:209], v170 offset:54272
	ds_read_b128 v[210:213], v170 offset:55296
	ds_read_b128 v[214:217], v170 offset:56320
	global_load_lds_dwordx4 v[218:219], off
	s_add_i32 m0, s38, 0x2000
	s_add_u32 s46, s46, 0x40080
	v_lshl_add_u64 v[218:219], v[220:221], 0, s[30:31]
	s_addc_u32 s47, s47, 0
	s_add_i32 s38, s39, s75
	global_load_lds_dwordx4 v[218:219], off
	v_lshl_add_u64 v[218:219], s[46:47], 0, v[134:135]
	s_mov_b32 m0, s38
	s_nop 0
	global_load_lds_dwordx4 v[218:219], off
	v_lshl_add_u64 v[218:219], s[46:47], 0, v[130:131]
	s_add_i32 m0, s38, 0x2000
	s_nop 0
	global_load_lds_dwordx4 v[218:219], off
	v_lshl_add_u64 v[218:219], v[222:223], 0, s[30:31]
	s_mov_b32 m0, s80
	s_nop 0
	global_load_lds_dwordx4 v[218:219], off
	v_lshl_add_u64 v[218:219], v[224:225], 0, s[30:31]
	s_mov_b32 m0, s81
	s_nop 0
	global_load_lds_dwordx4 v[218:219], off
	s_waitcnt vmcnt(8)
	s_waitcnt lgkmcnt(0)
	s_barrier
	v_mfma_f32_16x16x32_bf16 v[58:61], v[142:145], v[180:183], v[58:61]
	v_mfma_f32_16x16x32_bf16 v[58:61], v[146:149], v[184:187], v[58:61]
	v_mfma_f32_16x16x32_bf16 v[42:45], v[142:145], v[188:191], v[42:45]
	v_mfma_f32_16x16x32_bf16 v[42:45], v[146:149], v[192:195], v[42:45]
	v_mfma_f32_16x16x32_bf16 v[26:29], v[142:145], v[202:205], v[26:29]
	v_mfma_f32_16x16x32_bf16 v[26:29], v[146:149], v[206:209], v[26:29]
	v_mfma_f32_16x16x32_bf16 v[10:13], v[142:145], v[210:213], v[10:13]
	v_mfma_f32_16x16x32_bf16 v[10:13], v[146:149], v[214:217], v[10:13]
	v_mfma_f32_16x16x32_bf16 v[62:65], v[150:153], v[180:183], v[62:65]
	v_mfma_f32_16x16x32_bf16 v[62:65], v[154:157], v[184:187], v[62:65]
	v_mfma_f32_16x16x32_bf16 v[46:49], v[150:153], v[188:191], v[46:49]
	v_mfma_f32_16x16x32_bf16 v[46:49], v[154:157], v[192:195], v[46:49]
	v_mfma_f32_16x16x32_bf16 v[30:33], v[150:153], v[202:205], v[30:33]
	v_mfma_f32_16x16x32_bf16 v[30:33], v[154:157], v[206:209], v[30:33]
	v_mfma_f32_16x16x32_bf16 v[14:17], v[150:153], v[210:213], v[14:17]
	v_mfma_f32_16x16x32_bf16 v[14:17], v[154:157], v[214:217], v[14:17]
	v_mfma_f32_16x16x32_bf16 v[50:53], v[158:161], v[180:183], v[50:53]
	v_mfma_f32_16x16x32_bf16 v[50:53], v[162:165], v[184:187], v[50:53]
	v_mfma_f32_16x16x32_bf16 v[34:37], v[158:161], v[188:191], v[34:37]
	v_mfma_f32_16x16x32_bf16 v[34:37], v[162:165], v[192:195], v[34:37]
	v_mfma_f32_16x16x32_bf16 v[18:21], v[158:161], v[202:205], v[18:21]
	v_mfma_f32_16x16x32_bf16 v[18:21], v[162:165], v[206:209], v[18:21]
	v_mfma_f32_16x16x32_bf16 v[2:5], v[158:161], v[210:213], v[2:5]
	v_mfma_f32_16x16x32_bf16 v[2:5], v[162:165], v[214:217], v[2:5]
	v_mfma_f32_16x16x32_bf16 v[54:57], v[172:175], v[180:183], v[54:57]
	v_mfma_f32_16x16x32_bf16 v[54:57], v[176:179], v[184:187], v[54:57]
	v_mfma_f32_16x16x32_bf16 v[38:41], v[172:175], v[188:191], v[38:41]
	v_mfma_f32_16x16x32_bf16 v[38:41], v[176:179], v[192:195], v[38:41]
	v_mfma_f32_16x16x32_bf16 v[22:25], v[172:175], v[202:205], v[22:25]
	v_mfma_f32_16x16x32_bf16 v[22:25], v[176:179], v[206:209], v[22:25]
	v_mfma_f32_16x16x32_bf16 v[6:9], v[172:175], v[210:213], v[6:9]
	v_mfma_f32_16x16x32_bf16 v[6:9], v[176:179], v[214:217], v[6:9]
	s_barrier
	s_add_i32 s84, s84, 2
	s_add_u32 s48, s48, 0x100
	s_addc_u32 s49, s49, 0
	s_add_u32 s53, s53, 0x100
	s_addc_u32 s69, s69, 0
	s_cmp_gt_u32 s84, 13
	s_cbranch_scc0 .LBB0_408
	s_and_b64 vcc, exec, s[64:65]
	s_cbranch_vccz .LBB0_411
	s_barrier
